# MFMA order: consecutive MFMAs share the accumulator or one A/B operand (k order reversed for alternate accumulators)
# speedup vs baseline: 1.0159x; 1.0055x over previous
; #define PG8_STAGE(bufoff, gbase, voff) do { _Pragma("unroll") for (int _i = 0; _i < 2; ++_i) \
;         __builtin_amdgcn_global_load_lds((const unsigned*)((const char*)(gbase) + (voff)[_i]), (PG8_LAS unsigned*)(lds + (bufoff) + ldsw + _i * 8192), 16, 0, 0); } while (0)
; #define PG8_LDA(dst, b, h) do { _Pragma("unroll") for (int m = 0; m < 4; ++m) _Pragma("unroll") for (int k = 0; k < 2; ++k) dst[m][k] = *(const PG8_LAS bf16x8*)(lds + PG8_SA(b, h) + aoff + m * 2048 + k * 1024); } while (0)
; #define PG8_MMA(ai, bj, At, Bt) do { __builtin_amdgcn_s_setprio(1); _Pragma("unroll") for (int m = 0; m < 4; ++m) _Pragma("unroll") for (int n = 0; n < 2; ++n) _Pragma("unroll") for (int k = 0; k < 2; ++k) \
;         acc[ai][bj][m][n] = __builtin_amdgcn_mfma_f32_16x16x32_bf16(Bt[n][k], At[m][k], acc[ai][bj][m][n], 0, 0, 0); __builtin_amdgcn_s_setprio(0); } while (0)
; #define PG8_WAIT_V(n) asm volatile("s_waitcnt vmcnt(" #n ")" ::: "memory")
; #define PG8_WAIT_L(n) asm volatile("s_waitcnt lgkmcnt(" #n ")" ::: "memory")
; #define PG8_BAR __builtin_amdgcn_s_barrier()
; #define PG8_SCHED __builtin_amdgcn_sched_barrier(0)
; template <class Epi, class Sched, bool ALIGN_EPI = true>
; __device__ __forceinline__ void gemm_phase(PG8_LAS unsigned char* lds, const Gemm g, const Sched& S, const Epi& E, const int tid) {
;     ...
;             PG8_WAIT_V(8); PG8_WAIT_L(0); PG8_BAR; PG8_MMA(0, 0, At, B0); PG8_MMA(0, 1, At, B1); PG8_BAR; PG8_SCHED;
;             PG8_LDA(At, 0, 1); PG8_STAGE(PG8_SB(0, 0), b2, voffB); PG8_STAGE(PG8_SB(0, 1), b2 + hstepB, voffB); PG8_STAGE(PG8_SA(0, 0), a2, voffA);
;             PG8_WAIT_V(8); PG8_WAIT_L(0); PG8_BAR; PG8_MMA(1, 0, At, B0); PG8_MMA(1, 1, At, B1); PG8_BAR; PG8_SCHED;
.LBB0_426:
	s_add_u32 s15, s12, 0xfff80080
	s_addc_u32 s16, s13, -1
	s_add_i32 s17, 0, 0x10000
	s_cmp_eq_u32 s53, 4
	s_cselect_b32 s63, s1, s16
	s_cselect_b32 s62, s5, s15
	s_cselect_b32 s23, s8, s21
	s_cselect_b32 s22, s9, s20
	s_add_i32 s15, 0, 0x14000
	v_add_u32_e32 v72, s17, v251
	v_add_u32_e32 v136, s15, v251
	ds_read_b128 v[60:63], v72
	ds_read_b128 v[64:67], v72 offset:1024
	ds_read_b128 v[68:71], v72 offset:2048
	ds_read_b128 v[72:75], v72 offset:3072
	ds_read_b128 v[100:103], v136
	ds_read_b128 v[112:115], v136 offset:1024
	ds_read_b128 v[116:119], v136 offset:2048
	ds_read_b128 v[136:139], v136 offset:3072
	s_add_i32 m0, s11, 0xc000
	ds_read_b128 v[140:143], v252
	ds_read_b128 v[152:155], v252 offset:1024
	ds_read_b128 v[156:159], v252 offset:2048
	ds_read_b128 v[168:171], v252 offset:3072
	ds_read_b128 v[172:175], v252 offset:4096
	ds_read_b128 v[184:187], v252 offset:5120
	ds_read_b128 v[188:191], v252 offset:6144
	ds_read_b128 v[192:195], v252 offset:7168
	global_load_lds_dwordx4 v216, s[12:13]
	s_add_i32 m0, s11, 0xe000
	s_nop 0
	global_load_lds_dwordx4 v218, s[12:13]
	s_waitcnt vmcnt(8)
	s_waitcnt lgkmcnt(0)
	s_barrier
	s_waitcnt lgkmcnt(0)
	v_mfma_f32_16x16x32_bf16 v[180:183], v[60:63], v[140:143], v[180:183]
	v_mfma_f32_16x16x32_bf16 v[180:183], v[64:67], v[152:155], v[180:183]
	v_mfma_f32_16x16x32_bf16 v[176:179], v[72:75], v[152:155], v[176:179]
	v_mfma_f32_16x16x32_bf16 v[176:179], v[68:71], v[140:143], v[176:179]
	v_mfma_f32_16x16x32_bf16 v[144:147], v[68:71], v[156:159], v[144:147]
	v_mfma_f32_16x16x32_bf16 v[144:147], v[72:75], v[168:171], v[144:147]
	v_mfma_f32_16x16x32_bf16 v[148:151], v[64:67], v[168:171], v[148:151]
	v_mfma_f32_16x16x32_bf16 v[148:151], v[60:63], v[156:159], v[148:151]
	v_mfma_f32_16x16x32_bf16 v[124:127], v[60:63], v[172:175], v[124:127]
	v_mfma_f32_16x16x32_bf16 v[124:127], v[64:67], v[184:187], v[124:127]
	v_mfma_f32_16x16x32_bf16 v[120:123], v[72:75], v[184:187], v[120:123]
	v_mfma_f32_16x16x32_bf16 v[120:123], v[68:71], v[172:175], v[120:123]
	v_mfma_f32_16x16x32_bf16 v[92:95], v[68:71], v[188:191], v[92:95]
	v_mfma_f32_16x16x32_bf16 v[92:95], v[72:75], v[192:195], v[92:95]
	v_mfma_f32_16x16x32_bf16 v[96:99], v[64:67], v[192:195], v[96:99]
	v_mfma_f32_16x16x32_bf16 v[96:99], v[60:63], v[188:191], v[96:99]
	v_mfma_f32_16x16x32_bf16 v[164:167], v[100:103], v[140:143], v[164:167]
	v_mfma_f32_16x16x32_bf16 v[132:135], v[100:103], v[156:159], v[132:135]
	v_mfma_f32_16x16x32_bf16 v[128:131], v[116:119], v[156:159], v[128:131]
	v_mfma_f32_16x16x32_bf16 v[108:111], v[100:103], v[172:175], v[108:111]
	v_mfma_f32_16x16x32_bf16 v[104:107], v[116:119], v[172:175], v[104:107]
	v_mfma_f32_16x16x32_bf16 v[88:91], v[100:103], v[188:191], v[88:91]
	v_mfma_f32_16x16x32_bf16 v[84:87], v[116:119], v[188:191], v[84:87]
	v_mfma_f32_16x16x32_bf16 v[164:167], v[112:115], v[152:155], v[164:167]
	v_mfma_f32_16x16x32_bf16 v[140:143], v[116:119], v[140:143], v[160:163]
	v_mfma_f32_16x16x32_bf16 v[132:135], v[112:115], v[168:171], v[132:135]
	v_mfma_f32_16x16x32_bf16 v[128:131], v[136:139], v[168:171], v[128:131]
	v_mfma_f32_16x16x32_bf16 v[108:111], v[112:115], v[184:187], v[108:111]
	v_mfma_f32_16x16x32_bf16 v[104:107], v[136:139], v[184:187], v[104:107]
	v_mfma_f32_16x16x32_bf16 v[88:91], v[112:115], v[192:195], v[88:91]
	v_mfma_f32_16x16x32_bf16 v[84:87], v[136:139], v[192:195], v[84:87]
	v_mfma_f32_16x16x32_bf16 v[140:143], v[136:139], v[152:155], v[140:143]
	s_barrier
	s_add_i32 s16, s17, s67
	s_mov_b32 m0, s16
	ds_read_b128 v[152:155], v252 offset:16384
	ds_read_b128 v[156:159], v252 offset:17408
	ds_read_b128 v[160:163], v252 offset:18432
	ds_read_b128 v[168:171], v252 offset:19456
	ds_read_b128 v[172:175], v252 offset:20480
	ds_read_b128 v[184:187], v252 offset:21504
	ds_read_b128 v[188:191], v252 offset:22528
	ds_read_b128 v[192:195], v252 offset:23552
	global_load_lds_dwordx4 v2, s[22:23]
	s_add_i32 m0, s16, 0x2000
	s_add_u32 s78, s22, 0x20000
	s_addc_u32 s79, s23, 0
	s_add_i32 s15, s15, s67
	global_load_lds_dwordx4 v210, s[22:23]
	s_mov_b32 m0, s15
	s_nop 0
	global_load_lds_dwordx4 v2, s[78:79]
	s_add_i32 m0, s15, 0x2000
	s_nop 0
	global_load_lds_dwordx4 v210, s[78:79]
	s_mov_b32 m0, s11
	s_nop 0
	global_load_lds_dwordx4 v214, s[62:63]
	s_mov_b32 m0, s68
	s_nop 0
	global_load_lds_dwordx4 v212, s[62:63]
	s_waitcnt vmcnt(8)
	s_waitcnt lgkmcnt(0)
	s_barrier
	s_waitcnt lgkmcnt(0)
	v_mfma_f32_16x16x32_bf16 v[80:83], v[60:63], v[152:155], v[80:83]
	v_mfma_f32_16x16x32_bf16 v[80:83], v[64:67], v[156:159], v[80:83]
	v_mfma_f32_16x16x32_bf16 v[76:79], v[72:75], v[156:159], v[76:79]
	v_mfma_f32_16x16x32_bf16 v[76:79], v[68:71], v[152:155], v[76:79]
	v_mfma_f32_16x16x32_bf16 v[44:47], v[68:71], v[160:163], v[44:47]
	v_mfma_f32_16x16x32_bf16 v[44:47], v[72:75], v[168:171], v[44:47]
	v_mfma_f32_16x16x32_bf16 v[48:51], v[64:67], v[168:171], v[48:51]
	v_mfma_f32_16x16x32_bf16 v[48:51], v[60:63], v[160:163], v[48:51]
	v_mfma_f32_16x16x32_bf16 v[32:35], v[60:63], v[172:175], v[32:35]
	v_mfma_f32_16x16x32_bf16 v[32:35], v[64:67], v[184:187], v[32:35]
	v_mfma_f32_16x16x32_bf16 v[28:31], v[72:75], v[184:187], v[28:31]
	v_mfma_f32_16x16x32_bf16 v[28:31], v[68:71], v[172:175], v[28:31]
	v_mfma_f32_16x16x32_bf16 v[12:15], v[68:71], v[188:191], v[12:15]
	v_mfma_f32_16x16x32_bf16 v[12:15], v[72:75], v[192:195], v[12:15]
	v_mfma_f32_16x16x32_bf16 v[16:19], v[64:67], v[192:195], v[16:19]
	v_mfma_f32_16x16x32_bf16 v[16:19], v[60:63], v[188:191], v[16:19]
	v_mfma_f32_16x16x32_bf16 v[56:59], v[100:103], v[152:155], v[56:59]
	v_mfma_f32_16x16x32_bf16 v[56:59], v[112:115], v[156:159], v[56:59]
	v_mfma_f32_16x16x32_bf16 v[52:55], v[136:139], v[156:159], v[52:55]
	v_mfma_f32_16x16x32_bf16 v[52:55], v[116:119], v[152:155], v[52:55]
	v_mfma_f32_16x16x32_bf16 v[36:39], v[116:119], v[160:163], v[36:39]
	v_mfma_f32_16x16x32_bf16 v[36:39], v[136:139], v[168:171], v[36:39]
	v_mfma_f32_16x16x32_bf16 v[40:43], v[112:115], v[168:171], v[40:43]
	v_mfma_f32_16x16x32_bf16 v[40:43], v[100:103], v[160:163], v[40:43]
	v_mfma_f32_16x16x32_bf16 v[24:27], v[100:103], v[172:175], v[24:27]
	v_mfma_f32_16x16x32_bf16 v[24:27], v[112:115], v[184:187], v[24:27]
	v_mfma_f32_16x16x32_bf16 v[20:23], v[136:139], v[184:187], v[20:23]
	v_mfma_f32_16x16x32_bf16 v[20:23], v[116:119], v[172:175], v[20:23]
	v_mfma_f32_16x16x32_bf16 v[4:7], v[116:119], v[188:191], v[4:7]
	v_mfma_f32_16x16x32_bf16 v[4:7], v[136:139], v[192:195], v[4:7]
	v_mfma_f32_16x16x32_bf16 v[8:11], v[112:115], v[192:195], v[8:11]
	v_mfma_f32_16x16x32_bf16 v[8:11], v[100:103], v[188:191], v[8:11]
	s_barrier
; #define PG8_STAGE(bufoff, gbase, voff) do { _Pragma("unroll") for (int _i = 0; _i < 2; ++_i) \
;         __builtin_amdgcn_global_load_lds((const unsigned*)((const char*)(gbase) + (voff)[_i]), (PG8_LAS unsigned*)(lds + (bufoff) + ldsw + _i * 8192), 16, 0, 0); } while (0)
; #define PG8_LDA(dst, b, h) do { _Pragma("unroll") for (int m = 0; m < 4; ++m) _Pragma("unroll") for (int k = 0; k < 2; ++k) dst[m][k] = *(const PG8_LAS bf16x8*)(lds + PG8_SA(b, h) + aoff + m * 2048 + k * 1024); } while (0)
; #define PG8_LDB(dst, b, h) do { _Pragma("unroll") for (int n = 0; n < 2; ++n) _Pragma("unroll") for (int k = 0; k < 2; ++k) dst[n][k] = *(const PG8_LAS bf16x8*)(lds + PG8_SB(b, h) + boff + n * 2048 + k * 1024); } while (0)
; #define PG8_MMA(ai, bj, At, Bt) do { __builtin_amdgcn_s_setprio(1); _Pragma("unroll") for (int m = 0; m < 4; ++m) _Pragma("unroll") for (int n = 0; n < 2; ++n) _Pragma("unroll") for (int k = 0; k < 2; ++k) \
;         acc[ai][bj][m][n] = __builtin_amdgcn_mfma_f32_16x16x32_bf16(Bt[n][k], At[m][k], acc[ai][bj][m][n], 0, 0, 0); __builtin_amdgcn_s_setprio(0); } while (0)
; #define PG8_WAIT_V(n) asm volatile("s_waitcnt vmcnt(" #n ")" ::: "memory")
; #define PG8_WAIT_L(n) asm volatile("s_waitcnt lgkmcnt(" #n ")" ::: "memory")
; #define PG8_BAR __builtin_amdgcn_s_barrier()
; #define PG8_SCHED __builtin_amdgcn_sched_barrier(0)
; template <class Epi, class Sched, bool ALIGN_EPI = true>
; __device__ __forceinline__ void gemm_phase(PG8_LAS unsigned char* lds, const Gemm g, const Sched& S, const Epi& E, const int tid) {
;     ...
;             PG8_LDB(B0, 1, 0); PG8_LDB(B1, 1, 1); PG8_SCHED; PG8_LDA(At, 1, 0); PG8_STAGE(PG8_SA(0, 1), a2 + hstepA, voffA);
;             PG8_WAIT_V(8); PG8_WAIT_L(0); PG8_BAR; PG8_MMA(0, 0, At, B0); PG8_MMA(0, 1, At, B1); PG8_BAR; PG8_SCHED;
;             PG8_LDA(At, 1, 1); PG8_STAGE(PG8_SB(1, 0), b3, voffB); PG8_STAGE(PG8_SB(1, 1), b3 + hstepB, voffB); PG8_STAGE(PG8_SA(1, 0), a3, voffA);
;             PG8_WAIT_V(8); PG8_WAIT_L(0); PG8_BAR; PG8_MMA(1, 0, At, B0); PG8_MMA(1, 1, At, B1); PG8_BAR; PG8_SCHED;
;         }
;         if constexpr (ALIGN_EPI) { if (wr == 0) PG8_BAR; }
;         E(acc, cur, wr, wc, fr, fq); S.done(cur);
;         if (!has_next) break;
	s_add_i32 s15, 0, 0x18000
	s_add_i32 s16, 0, 0x1c000
	v_add_u32_e32 v72, s15, v251
	v_add_u32_e32 v136, s16, v251
	ds_read_b128 v[60:63], v72
	ds_read_b128 v[64:67], v72 offset:1024
	ds_read_b128 v[68:71], v72 offset:2048
	ds_read_b128 v[72:75], v72 offset:3072
	ds_read_b128 v[100:103], v136
	ds_read_b128 v[112:115], v136 offset:1024
	ds_read_b128 v[116:119], v136 offset:2048
	ds_read_b128 v[136:139], v136 offset:3072
	s_add_u32 s62, s62, 0x80000
	s_addc_u32 s63, s63, 0
	s_mov_b32 m0, s69
	ds_read_b128 v[152:155], v252 offset:32768
	ds_read_b128 v[156:159], v252 offset:33792
	ds_read_b128 v[168:171], v252 offset:34816
	ds_read_b128 v[172:175], v252 offset:35840
	ds_read_b128 v[184:187], v252 offset:36864
	ds_read_b128 v[188:191], v252 offset:37888
	ds_read_b128 v[192:195], v252 offset:38912
	ds_read_b128 v[196:199], v252 offset:39936
	global_load_lds_dwordx4 v214, s[62:63]
	s_mov_b32 m0, s70
	s_nop 0
	global_load_lds_dwordx4 v212, s[62:63]
	s_waitcnt vmcnt(8)
	s_waitcnt lgkmcnt(0)
	s_barrier
	s_waitcnt lgkmcnt(0)
	v_mfma_f32_16x16x32_bf16 v[160:163], v[60:63], v[152:155], v[180:183]
	v_mfma_f32_16x16x32_bf16 v[180:183], v[64:67], v[156:159], v[160:163]
	v_mfma_f32_16x16x32_bf16 v[160:163], v[68:71], v[152:155], v[176:179]
	v_mfma_f32_16x16x32_bf16 v[148:151], v[60:63], v[168:171], v[148:151]
	v_mfma_f32_16x16x32_bf16 v[144:147], v[68:71], v[168:171], v[144:147]
	v_mfma_f32_16x16x32_bf16 v[124:127], v[60:63], v[184:187], v[124:127]
	v_mfma_f32_16x16x32_bf16 v[120:123], v[68:71], v[184:187], v[120:123]
	v_mfma_f32_16x16x32_bf16 v[96:99], v[60:63], v[192:195], v[96:99]
	v_mfma_f32_16x16x32_bf16 v[92:95], v[68:71], v[192:195], v[92:95]
	v_mfma_f32_16x16x32_bf16 v[176:179], v[72:75], v[156:159], v[160:163]
	v_mfma_f32_16x16x32_bf16 v[148:151], v[64:67], v[172:175], v[148:151]
	v_mfma_f32_16x16x32_bf16 v[144:147], v[72:75], v[172:175], v[144:147]
	v_mfma_f32_16x16x32_bf16 v[124:127], v[64:67], v[188:191], v[124:127]
	v_mfma_f32_16x16x32_bf16 v[120:123], v[72:75], v[188:191], v[120:123]
	v_mfma_f32_16x16x32_bf16 v[96:99], v[64:67], v[196:199], v[96:99]
	v_mfma_f32_16x16x32_bf16 v[92:95], v[72:75], v[196:199], v[92:95]
	v_mfma_f32_16x16x32_bf16 v[160:163], v[100:103], v[152:155], v[164:167]
	v_mfma_f32_16x16x32_bf16 v[140:143], v[116:119], v[152:155], v[140:143]
	v_mfma_f32_16x16x32_bf16 v[132:135], v[100:103], v[168:171], v[132:135]
	v_mfma_f32_16x16x32_bf16 v[128:131], v[116:119], v[168:171], v[128:131]
	v_mfma_f32_16x16x32_bf16 v[108:111], v[100:103], v[184:187], v[108:111]
	v_mfma_f32_16x16x32_bf16 v[104:107], v[116:119], v[184:187], v[104:107]
	v_mfma_f32_16x16x32_bf16 v[88:91], v[100:103], v[192:195], v[88:91]
	v_mfma_f32_16x16x32_bf16 v[84:87], v[116:119], v[192:195], v[84:87]
	v_mfma_f32_16x16x32_bf16 v[164:167], v[112:115], v[156:159], v[160:163]
	v_mfma_f32_16x16x32_bf16 v[160:163], v[136:139], v[156:159], v[140:143]
	v_mfma_f32_16x16x32_bf16 v[132:135], v[112:115], v[172:175], v[132:135]
	v_mfma_f32_16x16x32_bf16 v[128:131], v[136:139], v[172:175], v[128:131]
	v_mfma_f32_16x16x32_bf16 v[108:111], v[112:115], v[188:191], v[108:111]
	v_mfma_f32_16x16x32_bf16 v[104:107], v[136:139], v[188:191], v[104:107]
	v_mfma_f32_16x16x32_bf16 v[88:91], v[112:115], v[196:199], v[88:91]
	v_mfma_f32_16x16x32_bf16 v[84:87], v[136:139], v[196:199], v[84:87]
	s_barrier
	s_add_i32 s15, s15, s67
	s_mov_b32 m0, s15
	ds_read_b128 v[140:143], v252 offset:49152
	ds_read_b128 v[152:155], v252 offset:50176
	ds_read_b128 v[156:159], v252 offset:51200
	ds_read_b128 v[168:171], v252 offset:52224
	ds_read_b128 v[172:175], v252 offset:53248
	ds_read_b128 v[184:187], v252 offset:54272
	ds_read_b128 v[188:191], v252 offset:55296
	ds_read_b128 v[192:195], v252 offset:56320
	s_add_u32 s98, s22, 0x80
	s_addc_u32 s99, s23, 0
	global_load_lds_dwordx4 v2, s[98:99]
	s_add_i32 m0, s15, 0x2000
	s_add_u32 s22, s22, 0x20080
	s_addc_u32 s23, s23, 0
	s_add_i32 s15, s16, s67
	global_load_lds_dwordx4 v210, s[98:99]
	s_mov_b32 m0, s15
	s_nop 0
	global_load_lds_dwordx4 v2, s[22:23]
	s_add_i32 m0, s15, 0x2000
	s_nop 0
	global_load_lds_dwordx4 v210, s[22:23]
	s_mov_b32 m0, s75
	s_nop 0
	s_add_u32 s98, s62, 0xfff80080
	s_addc_u32 s99, s63, -1
	global_load_lds_dwordx4 v214, s[98:99]
	s_mov_b32 m0, s76
	s_nop 0
	global_load_lds_dwordx4 v212, s[98:99]
	s_waitcnt vmcnt(8)
	s_waitcnt lgkmcnt(0)
	s_barrier
	s_waitcnt lgkmcnt(0)
	v_mfma_f32_16x16x32_bf16 v[80:83], v[60:63], v[140:143], v[80:83]
	v_mfma_f32_16x16x32_bf16 v[80:83], v[64:67], v[152:155], v[80:83]
	v_mfma_f32_16x16x32_bf16 v[76:79], v[72:75], v[152:155], v[76:79]
	v_mfma_f32_16x16x32_bf16 v[76:79], v[68:71], v[140:143], v[76:79]
	v_mfma_f32_16x16x32_bf16 v[44:47], v[68:71], v[156:159], v[44:47]
	v_mfma_f32_16x16x32_bf16 v[44:47], v[72:75], v[168:171], v[44:47]
	v_mfma_f32_16x16x32_bf16 v[48:51], v[64:67], v[168:171], v[48:51]
	v_mfma_f32_16x16x32_bf16 v[48:51], v[60:63], v[156:159], v[48:51]
	v_mfma_f32_16x16x32_bf16 v[32:35], v[60:63], v[172:175], v[32:35]
	v_mfma_f32_16x16x32_bf16 v[32:35], v[64:67], v[184:187], v[32:35]
	v_mfma_f32_16x16x32_bf16 v[28:31], v[72:75], v[184:187], v[28:31]
	v_mfma_f32_16x16x32_bf16 v[28:31], v[68:71], v[172:175], v[28:31]
	v_mfma_f32_16x16x32_bf16 v[12:15], v[68:71], v[188:191], v[12:15]
	v_mfma_f32_16x16x32_bf16 v[12:15], v[72:75], v[192:195], v[12:15]
	v_mfma_f32_16x16x32_bf16 v[16:19], v[64:67], v[192:195], v[16:19]
	v_mfma_f32_16x16x32_bf16 v[16:19], v[60:63], v[188:191], v[16:19]
	v_mfma_f32_16x16x32_bf16 v[56:59], v[100:103], v[140:143], v[56:59]
	v_mfma_f32_16x16x32_bf16 v[56:59], v[112:115], v[152:155], v[56:59]
	v_mfma_f32_16x16x32_bf16 v[52:55], v[136:139], v[152:155], v[52:55]
	v_mfma_f32_16x16x32_bf16 v[52:55], v[116:119], v[140:143], v[52:55]
	v_mfma_f32_16x16x32_bf16 v[36:39], v[116:119], v[156:159], v[36:39]
	v_mfma_f32_16x16x32_bf16 v[36:39], v[136:139], v[168:171], v[36:39]
	v_mfma_f32_16x16x32_bf16 v[40:43], v[112:115], v[168:171], v[40:43]
	v_mfma_f32_16x16x32_bf16 v[40:43], v[100:103], v[156:159], v[40:43]
	v_mfma_f32_16x16x32_bf16 v[24:27], v[100:103], v[172:175], v[24:27]
	v_mfma_f32_16x16x32_bf16 v[24:27], v[112:115], v[184:187], v[24:27]
	v_mfma_f32_16x16x32_bf16 v[20:23], v[136:139], v[184:187], v[20:23]
	v_mfma_f32_16x16x32_bf16 v[20:23], v[116:119], v[172:175], v[20:23]
	v_mfma_f32_16x16x32_bf16 v[4:7], v[116:119], v[188:191], v[4:7]
	v_mfma_f32_16x16x32_bf16 v[4:7], v[136:139], v[192:195], v[4:7]
	v_mfma_f32_16x16x32_bf16 v[8:11], v[112:115], v[192:195], v[8:11]
	v_mfma_f32_16x16x32_bf16 v[8:11], v[100:103], v[188:191], v[8:11]
	s_barrier
	s_add_i32 s53, s53, 2
	s_add_u32 s12, s12, 0x100
	s_addc_u32 s13, s13, 0
	s_add_u32 s20, s20, 0x100
	s_addc_u32 s21, s21, 0
	s_cmp_gt_u32 s53, 5
	s_cbranch_scc0 .LBB0_426
	s_and_b64 vcc, exec, s[48:49]
	s_cbranch_vccz .LBB0_429
	s_barrier

; #define PG8_STAGE(bufoff, gbase, voff) do { _Pragma("unroll") for (int _i = 0; _i < 2; ++_i) \
;         __builtin_amdgcn_global_load_lds((const unsigned*)((const char*)(gbase) + (voff)[_i]), (PG8_LAS unsigned*)(lds + (bufoff) + ldsw + _i * 8192), 16, 0, 0); } while (0)
; #define PG8_LDA(dst, b, h) do { _Pragma("unroll") for (int m = 0; m < 4; ++m) _Pragma("unroll") for (int k = 0; k < 2; ++k) dst[m][k] = *(const PG8_LAS bf16x8*)(lds + PG8_SA(b, h) + aoff + m * 2048 + k * 1024); } while (0)
; #define PG8_LDB(dst, b, h) do { _Pragma("unroll") for (int n = 0; n < 2; ++n) _Pragma("unroll") for (int k = 0; k < 2; ++k) dst[n][k] = *(const PG8_LAS bf16x8*)(lds + PG8_SB(b, h) + boff + n * 2048 + k * 1024); } while (0)
; #define PG8_MMA(ai, bj, At, Bt) do { __builtin_amdgcn_s_setprio(1); _Pragma("unroll") for (int m = 0; m < 4; ++m) _Pragma("unroll") for (int n = 0; n < 2; ++n) _Pragma("unroll") for (int k = 0; k < 2; ++k) \
;         acc[ai][bj][m][n] = __builtin_amdgcn_mfma_f32_16x16x32_bf16(Bt[n][k], At[m][k], acc[ai][bj][m][n], 0, 0, 0); __builtin_amdgcn_s_setprio(0); } while (0)
; #define PG8_WAIT_V(n) asm volatile("s_waitcnt vmcnt(" #n ")" ::: "memory")
; #define PG8_WAIT_L(n) asm volatile("s_waitcnt lgkmcnt(" #n ")" ::: "memory")
; #define PG8_BAR __builtin_amdgcn_s_barrier()
; #define PG8_SCHED __builtin_amdgcn_sched_barrier(0)
; template <class Epi, class Sched, bool ALIGN_EPI = true>
; __device__ __forceinline__ void gemm_phase(PG8_LAS unsigned char* lds, const Gemm g, const Sched& S, const Epi& E, const int tid) {
;     ...
;             PG8_LDB(B0, 0, 0); PG8_LDB(B1, 0, 1); PG8_SCHED; PG8_LDA(At, 0, 0); PG8_STAGE(PG8_SA(1, 1), a1 + hstepA, voffA);
;             PG8_WAIT_V(8); PG8_WAIT_L(0); PG8_BAR; PG8_MMA(0, 0, At, B0); PG8_MMA(0, 1, At, B1); PG8_BAR; PG8_SCHED;
;             PG8_LDA(At, 0, 1); PG8_STAGE(PG8_SB(0, 0), b2, voffB); PG8_STAGE(PG8_SB(0, 1), b2 + hstepB, voffB); PG8_STAGE(PG8_SA(0, 0), a2, voffA);
;             PG8_WAIT_V(8); PG8_WAIT_L(0); PG8_BAR; PG8_MMA(1, 0, At, B0); PG8_MMA(1, 1, At, B1); PG8_BAR; PG8_SCHED;
.LBB0_514:
	s_add_u32 s44, s42, 0xfff80080
	s_addc_u32 s45, s43, -1
	s_add_i32 s57, 0, 0x10000
	s_cmp_eq_u32 s56, 28
	s_cselect_b32 s47, s13, s45
	s_cselect_b32 s46, s52, s44
	s_cselect_b32 s45, s23, s55
	s_cselect_b32 s44, s53, s54
	s_add_i32 s60, 0, 0x14000
	v_add_u32_e32 v158, s57, v147
	v_add_u32_e32 v174, s60, v147
	ds_read_b128 v[142:145], v158
	ds_read_b128 v[150:153], v158 offset:1024
	ds_read_b128 v[154:157], v158 offset:2048
	ds_read_b128 v[158:161], v158 offset:3072
	ds_read_b128 v[162:165], v174
	ds_read_b128 v[166:169], v174 offset:1024
	ds_read_b128 v[170:173], v174 offset:2048
	ds_read_b128 v[174:177], v174 offset:3072
	s_add_i32 m0, s7, 0xc000
	ds_read_b128 v[178:181], v149
	ds_read_b128 v[182:185], v149 offset:1024
	ds_read_b128 v[186:189], v149 offset:2048
	ds_read_b128 v[190:193], v149 offset:3072
	ds_read_b128 v[194:197], v149 offset:4096
	ds_read_b128 v[198:201], v149 offset:5120
	ds_read_b128 v[202:205], v149 offset:6144
	ds_read_b128 v[210:213], v149 offset:7168
	global_load_lds_dwordx4 v138, s[42:43]
	s_add_i32 m0, s7, 0xe000
	s_nop 0
	global_load_lds_dwordx4 v140, s[42:43]
	s_waitcnt vmcnt(8)
	s_waitcnt lgkmcnt(0)
	s_barrier
	s_waitcnt lgkmcnt(0)
	v_mfma_f32_16x16x32_bf16 v[128:131], v[142:145], v[178:181], v[128:131]
	v_mfma_f32_16x16x32_bf16 v[128:131], v[150:153], v[182:185], v[128:131]
	v_mfma_f32_16x16x32_bf16 v[124:127], v[158:161], v[182:185], v[124:127]
	v_mfma_f32_16x16x32_bf16 v[124:127], v[154:157], v[178:181], v[124:127]
	v_mfma_f32_16x16x32_bf16 v[112:115], v[154:157], v[186:189], v[112:115]
	v_mfma_f32_16x16x32_bf16 v[112:115], v[158:161], v[190:193], v[112:115]
	v_mfma_f32_16x16x32_bf16 v[120:123], v[150:153], v[190:193], v[120:123]
	v_mfma_f32_16x16x32_bf16 v[120:123], v[142:145], v[186:189], v[120:123]
	v_mfma_f32_16x16x32_bf16 v[104:107], v[142:145], v[194:197], v[104:107]
	v_mfma_f32_16x16x32_bf16 v[104:107], v[150:153], v[198:201], v[104:107]
	v_mfma_f32_16x16x32_bf16 v[96:99], v[158:161], v[198:201], v[96:99]
	v_mfma_f32_16x16x32_bf16 v[96:99], v[154:157], v[194:197], v[96:99]
	v_mfma_f32_16x16x32_bf16 v[80:83], v[154:157], v[202:205], v[80:83]
	v_mfma_f32_16x16x32_bf16 v[80:83], v[158:161], v[210:213], v[80:83]
	v_mfma_f32_16x16x32_bf16 v[88:91], v[150:153], v[210:213], v[88:91]
	v_mfma_f32_16x16x32_bf16 v[88:91], v[142:145], v[202:205], v[88:91]
	v_mfma_f32_16x16x32_bf16 v[116:119], v[162:165], v[178:181], v[116:119]
	v_mfma_f32_16x16x32_bf16 v[116:119], v[166:169], v[182:185], v[116:119]
	v_mfma_f32_16x16x32_bf16 v[108:111], v[174:177], v[182:185], v[108:111]
	v_mfma_f32_16x16x32_bf16 v[108:111], v[170:173], v[178:181], v[108:111]
	v_mfma_f32_16x16x32_bf16 v[92:95], v[170:173], v[186:189], v[92:95]
	v_mfma_f32_16x16x32_bf16 v[92:95], v[174:177], v[190:193], v[92:95]
	v_mfma_f32_16x16x32_bf16 v[100:103], v[166:169], v[190:193], v[100:103]
	v_mfma_f32_16x16x32_bf16 v[100:103], v[162:165], v[186:189], v[100:103]
	v_mfma_f32_16x16x32_bf16 v[84:87], v[162:165], v[194:197], v[84:87]
	v_mfma_f32_16x16x32_bf16 v[84:87], v[166:169], v[198:201], v[84:87]
	v_mfma_f32_16x16x32_bf16 v[76:79], v[174:177], v[198:201], v[76:79]
	v_mfma_f32_16x16x32_bf16 v[76:79], v[170:173], v[194:197], v[76:79]
	v_mfma_f32_16x16x32_bf16 v[68:71], v[170:173], v[202:205], v[68:71]
	v_mfma_f32_16x16x32_bf16 v[68:71], v[174:177], v[210:213], v[68:71]
	v_mfma_f32_16x16x32_bf16 v[72:75], v[166:169], v[210:213], v[72:75]
	v_mfma_f32_16x16x32_bf16 v[72:75], v[162:165], v[202:205], v[72:75]
	s_barrier
	s_add_i32 s57, s57, s21
	s_mov_b32 m0, s57
	ds_read_b128 v[178:181], v149 offset:16384
	ds_read_b128 v[182:185], v149 offset:17408
	ds_read_b128 v[186:189], v149 offset:18432
	ds_read_b128 v[190:193], v149 offset:19456
	ds_read_b128 v[194:197], v149 offset:20480
	ds_read_b128 v[198:201], v149 offset:21504
	ds_read_b128 v[202:205], v149 offset:22528
	ds_read_b128 v[210:213], v149 offset:23552
	global_load_lds_dwordx4 v2, s[44:45]
	s_add_i32 m0, s57, 0x2000
	s_add_u32 s58, s44, 0x80000
	s_addc_u32 s59, s45, 0
	s_add_i32 s57, s60, s21
	global_load_lds_dwordx4 v132, s[44:45]
	s_mov_b32 m0, s57
	s_nop 0
	global_load_lds_dwordx4 v2, s[58:59]
	s_add_i32 m0, s57, 0x2000
	s_nop 0
	global_load_lds_dwordx4 v132, s[58:59]
	s_mov_b32 m0, s7
	s_nop 0
	global_load_lds_dwordx4 v136, s[46:47]
	s_mov_b32 m0, s11
	s_nop 0
	global_load_lds_dwordx4 v134, s[46:47]
	s_waitcnt vmcnt(8)
	s_waitcnt lgkmcnt(0)
	s_barrier
	s_waitcnt lgkmcnt(0)
	v_mfma_f32_16x16x32_bf16 v[64:67], v[142:145], v[178:181], v[64:67]
	v_mfma_f32_16x16x32_bf16 v[64:67], v[150:153], v[182:185], v[64:67]
	v_mfma_f32_16x16x32_bf16 v[60:63], v[158:161], v[182:185], v[60:63]
	v_mfma_f32_16x16x32_bf16 v[60:63], v[154:157], v[178:181], v[60:63]
	v_mfma_f32_16x16x32_bf16 v[48:51], v[154:157], v[186:189], v[48:51]
	v_mfma_f32_16x16x32_bf16 v[48:51], v[158:161], v[190:193], v[48:51]
	v_mfma_f32_16x16x32_bf16 v[56:59], v[150:153], v[190:193], v[56:59]
	v_mfma_f32_16x16x32_bf16 v[56:59], v[142:145], v[186:189], v[56:59]
	v_mfma_f32_16x16x32_bf16 v[40:43], v[142:145], v[194:197], v[40:43]
	v_mfma_f32_16x16x32_bf16 v[40:43], v[150:153], v[198:201], v[40:43]
	v_mfma_f32_16x16x32_bf16 v[32:35], v[158:161], v[198:201], v[32:35]
	v_mfma_f32_16x16x32_bf16 v[32:35], v[154:157], v[194:197], v[32:35]
	v_mfma_f32_16x16x32_bf16 v[16:19], v[154:157], v[202:205], v[16:19]
	v_mfma_f32_16x16x32_bf16 v[16:19], v[158:161], v[210:213], v[16:19]
	v_mfma_f32_16x16x32_bf16 v[24:27], v[150:153], v[210:213], v[24:27]
	v_mfma_f32_16x16x32_bf16 v[24:27], v[142:145], v[202:205], v[24:27]
	v_mfma_f32_16x16x32_bf16 v[52:55], v[162:165], v[178:181], v[52:55]
	v_mfma_f32_16x16x32_bf16 v[52:55], v[166:169], v[182:185], v[52:55]
	v_mfma_f32_16x16x32_bf16 v[44:47], v[174:177], v[182:185], v[44:47]
	v_mfma_f32_16x16x32_bf16 v[44:47], v[170:173], v[178:181], v[44:47]
	v_mfma_f32_16x16x32_bf16 v[28:31], v[170:173], v[186:189], v[28:31]
	v_mfma_f32_16x16x32_bf16 v[28:31], v[174:177], v[190:193], v[28:31]
	v_mfma_f32_16x16x32_bf16 v[36:39], v[166:169], v[190:193], v[36:39]
	v_mfma_f32_16x16x32_bf16 v[36:39], v[162:165], v[186:189], v[36:39]
	v_mfma_f32_16x16x32_bf16 v[20:23], v[162:165], v[194:197], v[20:23]
	v_mfma_f32_16x16x32_bf16 v[20:23], v[166:169], v[198:201], v[20:23]
	v_mfma_f32_16x16x32_bf16 v[12:15], v[174:177], v[198:201], v[12:15]
	v_mfma_f32_16x16x32_bf16 v[12:15], v[170:173], v[194:197], v[12:15]
	v_mfma_f32_16x16x32_bf16 v[4:7], v[170:173], v[202:205], v[4:7]
	v_mfma_f32_16x16x32_bf16 v[4:7], v[174:177], v[210:213], v[4:7]
	v_mfma_f32_16x16x32_bf16 v[8:11], v[166:169], v[210:213], v[8:11]
	v_mfma_f32_16x16x32_bf16 v[8:11], v[162:165], v[202:205], v[8:11]
	s_barrier
; #define PG8_STAGE(bufoff, gbase, voff) do { _Pragma("unroll") for (int _i = 0; _i < 2; ++_i) \
;         __builtin_amdgcn_global_load_lds((const unsigned*)((const char*)(gbase) + (voff)[_i]), (PG8_LAS unsigned*)(lds + (bufoff) + ldsw + _i * 8192), 16, 0, 0); } while (0)
; #define PG8_LDA(dst, b, h) do { _Pragma("unroll") for (int m = 0; m < 4; ++m) _Pragma("unroll") for (int k = 0; k < 2; ++k) dst[m][k] = *(const PG8_LAS bf16x8*)(lds + PG8_SA(b, h) + aoff + m * 2048 + k * 1024); } while (0)
; #define PG8_LDB(dst, b, h) do { _Pragma("unroll") for (int n = 0; n < 2; ++n) _Pragma("unroll") for (int k = 0; k < 2; ++k) dst[n][k] = *(const PG8_LAS bf16x8*)(lds + PG8_SB(b, h) + boff + n * 2048 + k * 1024); } while (0)
; #define PG8_MMA(ai, bj, At, Bt) do { __builtin_amdgcn_s_setprio(1); _Pragma("unroll") for (int m = 0; m < 4; ++m) _Pragma("unroll") for (int n = 0; n < 2; ++n) _Pragma("unroll") for (int k = 0; k < 2; ++k) \
;         acc[ai][bj][m][n] = __builtin_amdgcn_mfma_f32_16x16x32_bf16(Bt[n][k], At[m][k], acc[ai][bj][m][n], 0, 0, 0); __builtin_amdgcn_s_setprio(0); } while (0)
; #define PG8_WAIT_V(n) asm volatile("s_waitcnt vmcnt(" #n ")" ::: "memory")
; #define PG8_WAIT_L(n) asm volatile("s_waitcnt lgkmcnt(" #n ")" ::: "memory")
; #define PG8_BAR __builtin_amdgcn_s_barrier()
; #define PG8_SCHED __builtin_amdgcn_sched_barrier(0)
; template <class Epi, class Sched, bool ALIGN_EPI = true>
; __device__ __forceinline__ void gemm_phase(PG8_LAS unsigned char* lds, const Gemm g, const Sched& S, const Epi& E, const int tid) {
;     ...
;             PG8_LDB(B0, 1, 0); PG8_LDB(B1, 1, 1); PG8_SCHED; PG8_LDA(At, 1, 0); PG8_STAGE(PG8_SA(0, 1), a2 + hstepA, voffA);
;             PG8_WAIT_V(8); PG8_WAIT_L(0); PG8_BAR; PG8_MMA(0, 0, At, B0); PG8_MMA(0, 1, At, B1); PG8_BAR; PG8_SCHED;
;             PG8_LDA(At, 1, 1); PG8_STAGE(PG8_SB(1, 0), b3, voffB); PG8_STAGE(PG8_SB(1, 1), b3 + hstepB, voffB); PG8_STAGE(PG8_SA(1, 0), a3, voffA);
;             PG8_WAIT_V(8); PG8_WAIT_L(0); PG8_BAR; PG8_MMA(1, 0, At, B0); PG8_MMA(1, 1, At, B1); PG8_BAR; PG8_SCHED;
	s_add_i32 s57, 0, 0x18000
	s_add_i32 s58, 0, 0x1c000
	v_add_u32_e32 v158, s57, v147
	v_add_u32_e32 v174, s58, v147
	ds_read_b128 v[142:145], v158
	ds_read_b128 v[150:153], v158 offset:1024
	ds_read_b128 v[154:157], v158 offset:2048
	ds_read_b128 v[158:161], v158 offset:3072
	ds_read_b128 v[162:165], v174
	ds_read_b128 v[166:169], v174 offset:1024
	ds_read_b128 v[170:173], v174 offset:2048
	ds_read_b128 v[174:177], v174 offset:3072
	s_add_u32 s46, s46, 0x80000
	s_addc_u32 s47, s47, 0
	s_mov_b32 m0, s30
	ds_read_b128 v[178:181], v149 offset:32768
	ds_read_b128 v[182:185], v149 offset:33792
	ds_read_b128 v[186:189], v149 offset:34816
	ds_read_b128 v[190:193], v149 offset:35840
	ds_read_b128 v[194:197], v149 offset:36864
	ds_read_b128 v[198:201], v149 offset:37888
	ds_read_b128 v[202:205], v149 offset:38912
	ds_read_b128 v[210:213], v149 offset:39936
	global_load_lds_dwordx4 v136, s[46:47]
	s_mov_b32 m0, s48
	s_nop 0
	global_load_lds_dwordx4 v134, s[46:47]
	s_waitcnt vmcnt(8)
	s_waitcnt lgkmcnt(0)
	s_barrier
	s_waitcnt lgkmcnt(0)
	v_mfma_f32_16x16x32_bf16 v[128:131], v[142:145], v[178:181], v[128:131]
	v_mfma_f32_16x16x32_bf16 v[128:131], v[150:153], v[182:185], v[128:131]
	v_mfma_f32_16x16x32_bf16 v[124:127], v[158:161], v[182:185], v[124:127]
	v_mfma_f32_16x16x32_bf16 v[124:127], v[154:157], v[178:181], v[124:127]
	v_mfma_f32_16x16x32_bf16 v[112:115], v[154:157], v[186:189], v[112:115]
	v_mfma_f32_16x16x32_bf16 v[112:115], v[158:161], v[190:193], v[112:115]
	v_mfma_f32_16x16x32_bf16 v[120:123], v[150:153], v[190:193], v[120:123]
	v_mfma_f32_16x16x32_bf16 v[120:123], v[142:145], v[186:189], v[120:123]
	v_mfma_f32_16x16x32_bf16 v[104:107], v[142:145], v[194:197], v[104:107]
	v_mfma_f32_16x16x32_bf16 v[104:107], v[150:153], v[198:201], v[104:107]
	v_mfma_f32_16x16x32_bf16 v[96:99], v[158:161], v[198:201], v[96:99]
	v_mfma_f32_16x16x32_bf16 v[96:99], v[154:157], v[194:197], v[96:99]
	v_mfma_f32_16x16x32_bf16 v[80:83], v[154:157], v[202:205], v[80:83]
	v_mfma_f32_16x16x32_bf16 v[80:83], v[158:161], v[210:213], v[80:83]
	v_mfma_f32_16x16x32_bf16 v[88:91], v[150:153], v[210:213], v[88:91]
	v_mfma_f32_16x16x32_bf16 v[88:91], v[142:145], v[202:205], v[88:91]
	v_mfma_f32_16x16x32_bf16 v[116:119], v[162:165], v[178:181], v[116:119]
	v_mfma_f32_16x16x32_bf16 v[116:119], v[166:169], v[182:185], v[116:119]
	v_mfma_f32_16x16x32_bf16 v[108:111], v[174:177], v[182:185], v[108:111]
	v_mfma_f32_16x16x32_bf16 v[108:111], v[170:173], v[178:181], v[108:111]
	v_mfma_f32_16x16x32_bf16 v[92:95], v[170:173], v[186:189], v[92:95]
	v_mfma_f32_16x16x32_bf16 v[92:95], v[174:177], v[190:193], v[92:95]
	v_mfma_f32_16x16x32_bf16 v[100:103], v[166:169], v[190:193], v[100:103]
	v_mfma_f32_16x16x32_bf16 v[100:103], v[162:165], v[186:189], v[100:103]
	v_mfma_f32_16x16x32_bf16 v[84:87], v[162:165], v[194:197], v[84:87]
	v_mfma_f32_16x16x32_bf16 v[84:87], v[166:169], v[198:201], v[84:87]
	v_mfma_f32_16x16x32_bf16 v[76:79], v[174:177], v[198:201], v[76:79]
	v_mfma_f32_16x16x32_bf16 v[76:79], v[170:173], v[194:197], v[76:79]
	v_mfma_f32_16x16x32_bf16 v[68:71], v[170:173], v[202:205], v[68:71]
	v_mfma_f32_16x16x32_bf16 v[68:71], v[174:177], v[210:213], v[68:71]
	v_mfma_f32_16x16x32_bf16 v[72:75], v[166:169], v[210:213], v[72:75]
	v_mfma_f32_16x16x32_bf16 v[72:75], v[162:165], v[202:205], v[72:75]
	s_barrier
	s_add_u32 s96, s46, 0xfff80080
	s_addc_u32 s97, s47, -1
	s_add_i32 s46, s57, s21
	s_mov_b32 m0, s46
	ds_read_b128 v[178:181], v149 offset:49152
	ds_read_b128 v[182:185], v149 offset:50176
	ds_read_b128 v[186:189], v149 offset:51200
	ds_read_b128 v[190:193], v149 offset:52224
	ds_read_b128 v[194:197], v149 offset:53248
	ds_read_b128 v[198:201], v149 offset:54272
	ds_read_b128 v[202:205], v149 offset:55296
	ds_read_b128 v[210:213], v149 offset:56320
	s_add_u32 s98, s44, 0x80
	s_addc_u32 s99, s45, 0
	global_load_lds_dwordx4 v2, s[98:99]
	s_add_i32 m0, s46, 0x2000
	s_add_u32 s44, s44, 0x80080
	s_addc_u32 s45, s45, 0
	s_add_i32 s46, s58, s21
	global_load_lds_dwordx4 v132, s[98:99]
	s_mov_b32 m0, s46
	s_nop 0
	global_load_lds_dwordx4 v2, s[44:45]
	s_add_i32 m0, s46, 0x2000
	s_nop 0
	global_load_lds_dwordx4 v132, s[44:45]
	s_mov_b32 m0, s49
	s_nop 0
	global_load_lds_dwordx4 v136, s[96:97]
	s_mov_b32 m0, s50
	s_nop 0
	global_load_lds_dwordx4 v134, s[96:97]
	s_waitcnt vmcnt(8)
	s_waitcnt lgkmcnt(0)
	s_barrier
	s_waitcnt lgkmcnt(0)
	v_mfma_f32_16x16x32_bf16 v[64:67], v[142:145], v[178:181], v[64:67]
	v_mfma_f32_16x16x32_bf16 v[64:67], v[150:153], v[182:185], v[64:67]
	v_mfma_f32_16x16x32_bf16 v[60:63], v[158:161], v[182:185], v[60:63]
	v_mfma_f32_16x16x32_bf16 v[60:63], v[154:157], v[178:181], v[60:63]
	v_mfma_f32_16x16x32_bf16 v[48:51], v[154:157], v[186:189], v[48:51]
	v_mfma_f32_16x16x32_bf16 v[48:51], v[158:161], v[190:193], v[48:51]
	v_mfma_f32_16x16x32_bf16 v[56:59], v[150:153], v[190:193], v[56:59]
	v_mfma_f32_16x16x32_bf16 v[56:59], v[142:145], v[186:189], v[56:59]
	v_mfma_f32_16x16x32_bf16 v[40:43], v[142:145], v[194:197], v[40:43]
	v_mfma_f32_16x16x32_bf16 v[40:43], v[150:153], v[198:201], v[40:43]
	v_mfma_f32_16x16x32_bf16 v[32:35], v[158:161], v[198:201], v[32:35]
	v_mfma_f32_16x16x32_bf16 v[32:35], v[154:157], v[194:197], v[32:35]
	v_mfma_f32_16x16x32_bf16 v[16:19], v[154:157], v[202:205], v[16:19]
	v_mfma_f32_16x16x32_bf16 v[16:19], v[158:161], v[210:213], v[16:19]
	v_mfma_f32_16x16x32_bf16 v[24:27], v[150:153], v[210:213], v[24:27]
	v_mfma_f32_16x16x32_bf16 v[24:27], v[142:145], v[202:205], v[24:27]
	v_mfma_f32_16x16x32_bf16 v[52:55], v[162:165], v[178:181], v[52:55]
	v_mfma_f32_16x16x32_bf16 v[52:55], v[166:169], v[182:185], v[52:55]
	v_mfma_f32_16x16x32_bf16 v[44:47], v[174:177], v[182:185], v[44:47]
	v_mfma_f32_16x16x32_bf16 v[44:47], v[170:173], v[178:181], v[44:47]
	v_mfma_f32_16x16x32_bf16 v[28:31], v[170:173], v[186:189], v[28:31]
	v_mfma_f32_16x16x32_bf16 v[28:31], v[174:177], v[190:193], v[28:31]
	v_mfma_f32_16x16x32_bf16 v[36:39], v[166:169], v[190:193], v[36:39]
	v_mfma_f32_16x16x32_bf16 v[36:39], v[162:165], v[186:189], v[36:39]
	v_mfma_f32_16x16x32_bf16 v[20:23], v[162:165], v[194:197], v[20:23]
	v_mfma_f32_16x16x32_bf16 v[20:23], v[166:169], v[198:201], v[20:23]
	v_mfma_f32_16x16x32_bf16 v[12:15], v[174:177], v[198:201], v[12:15]
	v_mfma_f32_16x16x32_bf16 v[12:15], v[170:173], v[194:197], v[12:15]
	v_mfma_f32_16x16x32_bf16 v[4:7], v[170:173], v[202:205], v[4:7]
	v_mfma_f32_16x16x32_bf16 v[4:7], v[174:177], v[210:213], v[4:7]
	v_mfma_f32_16x16x32_bf16 v[8:11], v[166:169], v[210:213], v[8:11]
	v_mfma_f32_16x16x32_bf16 v[8:11], v[162:165], v[202:205], v[8:11]
	s_barrier
; __device__ __forceinline__ unsigned cvt_pk_bf16(float lo, float hi) { unsigned r; asm volatile("v_cvt_pk_bf16_f32 %0, %1, %2" : "=v"(r) : "v"(lo), "v"(hi)); return r; }
; #define PG8_WAIT_V(n) asm volatile("s_waitcnt vmcnt(" #n ")" ::: "memory")
; #define PG8_BAR __builtin_amdgcn_s_barrier()
;     __device__ __forceinline__ void operator()(const f32x4 (&acc)[2][2][4][2], const Unit& u, int wr, int wc, int fr, int fq) const {
;         const int row0 = u.pm * BM + wr * 64 + fr; const int col0 = u.pn * BM + wc * 32 + 8 * fq;
; #pragma unroll
;         for (int ai = 0; ai < 2; ++ai)
; #pragma unroll
;             for (int m = 0; m < 4; ++m) { bf16_t* rowp = O + (size_t)(row0 + ai * HALF + m * 16) * ldc + col0;
; #pragma unroll
;                 for (int bj = 0; bj < 2; ++bj) { const f32x4 v0 = acc[ai][bj][m][0], v1 = acc[ai][bj][m][1];
;                     u32x4 w; w.x = cvt_pk_bf16(v0[0], v0[1]); w.y = cvt_pk_bf16(v0[2], v0[3]); w.z = cvt_pk_bf16(v1[0], v1[1]); w.w = cvt_pk_bf16(v1[2], v1[3]);
;                     *(u32x4*)(rowp + bj * HALF) = w; } }
; template <class Epi, class Sched, bool ALIGN_EPI = true>
; __device__ __forceinline__ void gemm_phase(PG8_LAS unsigned char* lds, const Gemm g, const Sched& S, const Epi& E, const int tid) {
;     ...
;         }
;         if constexpr (ALIGN_EPI) { if (wr == 0) PG8_BAR; }
;         E(acc, cur, wr, wc, fr, fq); S.done(cur);
;         if (!has_next) break;
; #pragma unroll
;         for (int a = 0; a < 2; ++a)
; #pragma unroll
;             for (int b = 0; b < 2; ++b)
; #pragma unroll
;                 for (int m = 0; m < 4; ++m)
; #pragma unroll
;                     for (int n = 0; n < 2; ++n) acc[a][b][m][n] = (f32x4){0.f, 0.f, 0.f, 0.f};
;         cur = nxt; cA = nA; cB = nB; ++ui;
;         if constexpr (ALIGN_EPI) { if (wr == 1) PG8_BAR; }
;     }
;     PG8_WAIT_V(0);
;     if constexpr (!ALIGN_EPI) { if (wr == 0) PG8_BAR; }
;     PG8_BAR;
	s_add_i32 s56, s56, 2
	s_add_u32 s42, s42, 0x100
	s_addc_u32 s43, s43, 0
	s_add_u32 s54, s54, 0x100
	s_addc_u32 s55, s55, 0
	s_cmp_gt_u32 s56, 29
	s_cbranch_scc0 .LBB0_514
	v_lshl_or_b32 v144, s10, 8, v148
	v_lshl_add_u32 v152, s6, 8, v146
	v_ashrrev_i32_e32 v145, 31, v144
	v_mov_b64_e32 v[142:143], s[0:1]
	s_movk_i32 s3, 0x3200
	v_mad_i64_i32 v[150:151], s[42:43], v152, s3, v[142:143]
	v_lshlrev_b64 v[144:145], 1, v[144:145]
	v_lshl_add_u64 v[150:151], v[150:151], 0, v[144:145]
	v_cvt_pk_bf16_f32 v128, v128, v129
	v_cvt_pk_bf16_f32 v129, v130, v131
	v_cvt_pk_bf16_f32 v130, v124, v125
	v_cvt_pk_bf16_f32 v131, v126, v127
	global_store_dwordx4 v[150:151], v[128:131], off
	v_cvt_pk_bf16_f32 v116, v116, v117
	v_cvt_pk_bf16_f32 v117, v118, v119
	v_cvt_pk_bf16_f32 v118, v108, v109
	v_or_b32_e32 v108, 16, v152
	v_mad_i64_i32 v[108:109], s[42:43], v108, s3, v[142:143]
	v_cvt_pk_bf16_f32 v119, v110, v111
	global_store_dwordx4 v[150:151], v[116:119], off offset:256
	s_and_b64 vcc, exec, s[4:5]
	s_mov_b32 s10, s22
	v_lshl_add_u64 v[116:117], v[108:109], 0, v[144:145]
	v_cvt_pk_bf16_f32 v108, v120, v121
	v_cvt_pk_bf16_f32 v109, v122, v123
	v_cvt_pk_bf16_f32 v110, v112, v113
	v_cvt_pk_bf16_f32 v111, v114, v115
	global_store_dwordx4 v[116:117], v[108:111], off
	v_cvt_pk_bf16_f32 v100, v100, v101
	v_cvt_pk_bf16_f32 v101, v102, v103
	v_cvt_pk_bf16_f32 v102, v92, v93
	v_or_b32_e32 v92, 32, v152
	v_mad_i64_i32 v[92:93], s[42:43], v92, s3, v[142:143]
	v_cvt_pk_bf16_f32 v103, v94, v95
	global_store_dwordx4 v[116:117], v[100:103], off offset:256
	s_mov_b32 s6, s12
	s_mov_b64 s[44:45], s[40:41]
	v_lshl_add_u64 v[100:101], v[92:93], 0, v[144:145]
	v_cvt_pk_bf16_f32 v92, v104, v105
	v_cvt_pk_bf16_f32 v93, v106, v107
	v_cvt_pk_bf16_f32 v94, v96, v97
	v_cvt_pk_bf16_f32 v95, v98, v99
	global_store_dwordx4 v[100:101], v[92:95], off
	v_cvt_pk_bf16_f32 v84, v84, v85
	v_cvt_pk_bf16_f32 v85, v86, v87
	v_cvt_pk_bf16_f32 v86, v76, v77
	v_or_b32_e32 v76, 48, v152
	v_mad_i64_i32 v[76:77], s[42:43], v76, s3, v[142:143]
	v_cvt_pk_bf16_f32 v87, v78, v79
	global_store_dwordx4 v[100:101], v[84:87], off offset:256
	s_nop 1
	v_lshl_add_u64 v[84:85], v[76:77], 0, v[144:145]
	v_cvt_pk_bf16_f32 v76, v88, v89
	v_cvt_pk_bf16_f32 v77, v90, v91
	v_cvt_pk_bf16_f32 v78, v80, v81
	v_cvt_pk_bf16_f32 v79, v82, v83
	global_store_dwordx4 v[84:85], v[76:79], off
	v_cvt_pk_bf16_f32 v72, v72, v73
	v_cvt_pk_bf16_f32 v73, v74, v75
	v_cvt_pk_bf16_f32 v74, v68, v69
	v_add_u32_e32 v68, 0x80, v152
	v_mad_i64_i32 v[68:69], s[42:43], v68, s3, v[142:143]
	v_lshl_add_u64 v[68:69], v[68:69], 0, v[144:145]
	v_cvt_pk_bf16_f32 v75, v70, v71
	global_store_dwordx4 v[84:85], v[72:75], off offset:256
	v_cvt_pk_bf16_f32 v64, v64, v65
	v_cvt_pk_bf16_f32 v65, v66, v67
	v_cvt_pk_bf16_f32 v66, v60, v61
	v_cvt_pk_bf16_f32 v67, v62, v63
	global_store_dwordx4 v[68:69], v[64:67], off
	v_cvt_pk_bf16_f32 v52, v52, v53
	v_cvt_pk_bf16_f32 v53, v54, v55
	v_cvt_pk_bf16_f32 v54, v44, v45
	v_add_u32_e32 v44, 0x90, v152
	v_mad_i64_i32 v[44:45], s[42:43], v44, s3, v[142:143]
	v_cvt_pk_bf16_f32 v55, v46, v47
	global_store_dwordx4 v[68:69], v[52:55], off offset:256
	s_nop 1
	v_lshl_add_u64 v[52:53], v[44:45], 0, v[144:145]
	v_cvt_pk_bf16_f32 v44, v56, v57
	v_cvt_pk_bf16_f32 v45, v58, v59
	v_cvt_pk_bf16_f32 v46, v48, v49
	v_cvt_pk_bf16_f32 v47, v50, v51
	global_store_dwordx4 v[52:53], v[44:47], off
	v_cvt_pk_bf16_f32 v36, v36, v37
	v_cvt_pk_bf16_f32 v37, v38, v39
	v_cvt_pk_bf16_f32 v38, v28, v29
	v_add_u32_e32 v28, 0xa0, v152
	v_mad_i64_i32 v[28:29], s[42:43], v28, s3, v[142:143]
	v_cvt_pk_bf16_f32 v39, v30, v31
	global_store_dwordx4 v[52:53], v[36:39], off offset:256
	s_nop 1
	v_lshl_add_u64 v[36:37], v[28:29], 0, v[144:145]
	v_cvt_pk_bf16_f32 v28, v40, v41
	v_cvt_pk_bf16_f32 v29, v42, v43
	v_cvt_pk_bf16_f32 v30, v32, v33
	v_cvt_pk_bf16_f32 v31, v34, v35
	global_store_dwordx4 v[36:37], v[28:31], off
	v_cvt_pk_bf16_f32 v20, v20, v21
	v_cvt_pk_bf16_f32 v21, v22, v23
	v_cvt_pk_bf16_f32 v22, v12, v13
	v_add_u32_e32 v12, 0xb0, v152
	v_mad_i64_i32 v[12:13], s[42:43], v12, s3, v[142:143]
	v_cvt_pk_bf16_f32 v23, v14, v15
	global_store_dwordx4 v[36:37], v[20:23], off offset:256
	s_mov_b64 s[42:43], s[38:39]
	s_nop 0
	v_lshl_add_u64 v[20:21], v[12:13], 0, v[144:145]
	v_cvt_pk_bf16_f32 v12, v24, v25
	v_cvt_pk_bf16_f32 v13, v26, v27
	v_cvt_pk_bf16_f32 v14, v16, v17
	v_cvt_pk_bf16_f32 v15, v18, v19
	global_store_dwordx4 v[20:21], v[12:15], off
	v_cvt_pk_bf16_f32 v8, v8, v9
	v_cvt_pk_bf16_f32 v9, v10, v11
	v_cvt_pk_bf16_f32 v10, v4, v5
	v_cvt_pk_bf16_f32 v11, v6, v7
	global_store_dwordx4 v[20:21], v[8:11], off offset:256
	s_cbranch_vccz .LBB0_507
	s_waitcnt vmcnt(0)
	s_cmpk_gt_u32 s8, 0xff
	s_cbranch_scc1 .LBB0_518
	s_barrier

; #define PG8_STAGE(bufoff, gbase, voff) do { _Pragma("unroll") for (int _i = 0; _i < 2; ++_i) \
;         __builtin_amdgcn_global_load_lds((const unsigned*)((const char*)(gbase) + (voff)[_i]), (PG8_LAS unsigned*)(lds + (bufoff) + ldsw + _i * 8192), 16, 0, 0); } while (0)
; #define PG8_LDA(dst, b, h) do { _Pragma("unroll") for (int m = 0; m < 4; ++m) _Pragma("unroll") for (int k = 0; k < 2; ++k) dst[m][k] = *(const PG8_LAS bf16x8*)(lds + PG8_SA(b, h) + aoff + m * 2048 + k * 1024); } while (0)
; #define PG8_LDB(dst, b, h) do { _Pragma("unroll") for (int n = 0; n < 2; ++n) _Pragma("unroll") for (int k = 0; k < 2; ++k) dst[n][k] = *(const PG8_LAS bf16x8*)(lds + PG8_SB(b, h) + boff + n * 2048 + k * 1024); } while (0)
; #define PG8_MMA(ai, bj, At, Bt) do { __builtin_amdgcn_s_setprio(1); _Pragma("unroll") for (int m = 0; m < 4; ++m) _Pragma("unroll") for (int n = 0; n < 2; ++n) _Pragma("unroll") for (int k = 0; k < 2; ++k) \
;         acc[ai][bj][m][n] = __builtin_amdgcn_mfma_f32_16x16x32_bf16(Bt[n][k], At[m][k], acc[ai][bj][m][n], 0, 0, 0); __builtin_amdgcn_s_setprio(0); } while (0)
; #define PG8_WAIT_V(n) asm volatile("s_waitcnt vmcnt(" #n ")" ::: "memory")
; #define PG8_WAIT_L(n) asm volatile("s_waitcnt lgkmcnt(" #n ")" ::: "memory")
; #define PG8_BAR __builtin_amdgcn_s_barrier()
; #define PG8_SCHED __builtin_amdgcn_sched_barrier(0)
; template <class Epi, class Sched, bool ALIGN_EPI = true>
; __device__ __forceinline__ void gemm_phase(PG8_LAS unsigned char* lds, const Gemm g, const Sched& S, const Epi& E, const int tid) {
;     ...
;             PG8_LDB(B0, 0, 0); PG8_LDB(B1, 0, 1); PG8_SCHED; PG8_LDA(At, 0, 0); PG8_STAGE(PG8_SA(1, 1), a1 + hstepA, voffA);
;             PG8_WAIT_V(8); PG8_WAIT_L(0); PG8_BAR; PG8_MMA(0, 0, At, B0); PG8_MMA(0, 1, At, B1); PG8_BAR; PG8_SCHED;
;             PG8_LDA(At, 0, 1); PG8_STAGE(PG8_SB(0, 0), b2, voffB); PG8_STAGE(PG8_SB(0, 1), b2 + hstepB, voffB); PG8_STAGE(PG8_SA(0, 0), a2, voffA);
;             PG8_WAIT_V(8); PG8_WAIT_L(0); PG8_BAR; PG8_MMA(1, 0, At, B0); PG8_MMA(1, 1, At, B1); PG8_BAR; PG8_SCHED;
.LBB0_1087:
	s_add_i32 s45, s22, 2
	s_add_u32 s15, s12, 0xfff80080
	s_addc_u32 s16, s13, -1
	s_add_i32 s17, 0, 0x10000
	s_cmp_eq_u32 s1, s22
	s_cselect_b32 s55, s51, s16
	s_cselect_b32 s54, s50, s15
	s_cselect_b32 s23, s53, s21
	s_cselect_b32 s22, s52, s20
	s_add_i32 s15, 0, 0x14000
	v_add_u32_e32 v72, s17, v251
	v_add_u32_e32 v128, s15, v251
	ds_read_b128 v[56:59], v72
	ds_read_b128 v[64:67], v72 offset:1024
	ds_read_b128 v[68:71], v72 offset:2048
	ds_read_b128 v[72:75], v72 offset:3072
	ds_read_b128 v[92:95], v128
	ds_read_b128 v[104:107], v128 offset:1024
	ds_read_b128 v[116:119], v128 offset:2048
	ds_read_b128 v[128:131], v128 offset:3072
	s_add_i32 m0, s11, 0xc000
	ds_read_b128 v[140:143], v252
	ds_read_b128 v[152:155], v252 offset:1024
	ds_read_b128 v[156:159], v252 offset:2048
	ds_read_b128 v[160:163], v252 offset:3072
	ds_read_b128 v[172:175], v252 offset:4096
	ds_read_b128 v[184:187], v252 offset:5120
	ds_read_b128 v[188:191], v252 offset:6144
	ds_read_b128 v[192:195], v252 offset:7168
	global_load_lds_dwordx4 v216, s[12:13]
	s_add_i32 m0, s11, 0xe000
	s_nop 0
	global_load_lds_dwordx4 v218, s[12:13]
	s_waitcnt vmcnt(8)
	s_waitcnt lgkmcnt(0)
	s_barrier
	s_waitcnt lgkmcnt(0)
	v_mfma_f32_16x16x32_bf16 v[180:183], v[56:59], v[140:143], v[180:183]
	v_mfma_f32_16x16x32_bf16 v[180:183], v[64:67], v[152:155], v[180:183]
	v_mfma_f32_16x16x32_bf16 v[176:179], v[72:75], v[152:155], v[176:179]
	v_mfma_f32_16x16x32_bf16 v[176:179], v[68:71], v[140:143], v[176:179]
	v_mfma_f32_16x16x32_bf16 v[144:147], v[68:71], v[156:159], v[144:147]
	v_mfma_f32_16x16x32_bf16 v[144:147], v[72:75], v[160:163], v[144:147]
	v_mfma_f32_16x16x32_bf16 v[148:151], v[64:67], v[160:163], v[148:151]
	v_mfma_f32_16x16x32_bf16 v[148:151], v[56:59], v[156:159], v[148:151]
	v_mfma_f32_16x16x32_bf16 v[124:127], v[56:59], v[172:175], v[124:127]
	v_mfma_f32_16x16x32_bf16 v[124:127], v[64:67], v[184:187], v[124:127]
	v_mfma_f32_16x16x32_bf16 v[120:123], v[72:75], v[184:187], v[120:123]
	v_mfma_f32_16x16x32_bf16 v[120:123], v[68:71], v[172:175], v[120:123]
	v_mfma_f32_16x16x32_bf16 v[96:99], v[68:71], v[188:191], v[96:99]
	v_mfma_f32_16x16x32_bf16 v[96:99], v[72:75], v[192:195], v[96:99]
	v_mfma_f32_16x16x32_bf16 v[100:103], v[64:67], v[192:195], v[100:103]
	v_mfma_f32_16x16x32_bf16 v[100:103], v[56:59], v[188:191], v[100:103]
	v_mfma_f32_16x16x32_bf16 v[168:171], v[92:95], v[140:143], v[168:171]
	v_mfma_f32_16x16x32_bf16 v[136:139], v[92:95], v[156:159], v[136:139]
	v_mfma_f32_16x16x32_bf16 v[132:135], v[116:119], v[156:159], v[132:135]
	v_mfma_f32_16x16x32_bf16 v[112:115], v[92:95], v[172:175], v[112:115]
	v_mfma_f32_16x16x32_bf16 v[108:111], v[116:119], v[172:175], v[108:111]
	v_mfma_f32_16x16x32_bf16 v[88:91], v[92:95], v[188:191], v[88:91]
	v_mfma_f32_16x16x32_bf16 v[84:87], v[116:119], v[188:191], v[84:87]
	v_mfma_f32_16x16x32_bf16 v[168:171], v[104:107], v[152:155], v[168:171]
	v_mfma_f32_16x16x32_bf16 v[140:143], v[116:119], v[140:143], v[164:167]
	v_mfma_f32_16x16x32_bf16 v[136:139], v[104:107], v[160:163], v[136:139]
	v_mfma_f32_16x16x32_bf16 v[132:135], v[128:131], v[160:163], v[132:135]
	v_mfma_f32_16x16x32_bf16 v[112:115], v[104:107], v[184:187], v[112:115]
	v_mfma_f32_16x16x32_bf16 v[108:111], v[128:131], v[184:187], v[108:111]
	v_mfma_f32_16x16x32_bf16 v[88:91], v[104:107], v[192:195], v[88:91]
	v_mfma_f32_16x16x32_bf16 v[84:87], v[128:131], v[192:195], v[84:87]
	v_mfma_f32_16x16x32_bf16 v[140:143], v[128:131], v[152:155], v[140:143]
	s_barrier
	s_add_i32 s16, s17, s60
	s_mov_b32 m0, s16
	ds_read_b128 v[152:155], v252 offset:16384
	ds_read_b128 v[156:159], v252 offset:17408
	ds_read_b128 v[160:163], v252 offset:18432
	ds_read_b128 v[164:167], v252 offset:19456
	ds_read_b128 v[172:175], v252 offset:20480
	ds_read_b128 v[184:187], v252 offset:21504
	ds_read_b128 v[188:191], v252 offset:22528
	ds_read_b128 v[192:195], v252 offset:23552
	global_load_lds_dwordx4 v2, s[22:23]
	s_add_i32 m0, s16, 0x2000
	s_add_u32 s72, s22, 0x80000
	s_addc_u32 s73, s23, 0
	s_add_i32 s15, s15, s60
	global_load_lds_dwordx4 v214, s[22:23]
	s_mov_b32 m0, s15
	s_nop 0
	global_load_lds_dwordx4 v2, s[72:73]
	s_add_i32 m0, s15, 0x2000
	s_nop 0
	global_load_lds_dwordx4 v214, s[72:73]
	s_mov_b32 m0, s11
	s_nop 0
	global_load_lds_dwordx4 v210, s[54:55]
	s_mov_b32 m0, s61
	s_nop 0
	global_load_lds_dwordx4 v212, s[54:55]
	s_waitcnt vmcnt(8)
	s_waitcnt lgkmcnt(0)
	s_barrier
	s_waitcnt lgkmcnt(0)
	v_mfma_f32_16x16x32_bf16 v[80:83], v[56:59], v[152:155], v[80:83]
	v_mfma_f32_16x16x32_bf16 v[80:83], v[64:67], v[156:159], v[80:83]
	v_mfma_f32_16x16x32_bf16 v[76:79], v[72:75], v[156:159], v[76:79]
	v_mfma_f32_16x16x32_bf16 v[76:79], v[68:71], v[152:155], v[76:79]
	v_mfma_f32_16x16x32_bf16 v[44:47], v[68:71], v[160:163], v[44:47]
	v_mfma_f32_16x16x32_bf16 v[44:47], v[72:75], v[164:167], v[44:47]
	v_mfma_f32_16x16x32_bf16 v[48:51], v[64:67], v[164:167], v[48:51]
	v_mfma_f32_16x16x32_bf16 v[48:51], v[56:59], v[160:163], v[48:51]
	v_mfma_f32_16x16x32_bf16 v[32:35], v[56:59], v[172:175], v[32:35]
	v_mfma_f32_16x16x32_bf16 v[32:35], v[64:67], v[184:187], v[32:35]
	v_mfma_f32_16x16x32_bf16 v[28:31], v[72:75], v[184:187], v[28:31]
	v_mfma_f32_16x16x32_bf16 v[28:31], v[68:71], v[172:175], v[28:31]
	v_mfma_f32_16x16x32_bf16 v[12:15], v[68:71], v[188:191], v[12:15]
	v_mfma_f32_16x16x32_bf16 v[12:15], v[72:75], v[192:195], v[12:15]
	v_mfma_f32_16x16x32_bf16 v[16:19], v[64:67], v[192:195], v[16:19]
	v_mfma_f32_16x16x32_bf16 v[16:19], v[56:59], v[188:191], v[16:19]
	v_mfma_f32_16x16x32_bf16 v[52:55], v[116:119], v[152:155], v[52:55]
	v_mfma_f32_16x16x32_bf16 v[40:43], v[92:95], v[160:163], v[40:43]
	v_mfma_f32_16x16x32_bf16 v[36:39], v[116:119], v[160:163], v[36:39]
	v_mfma_f32_16x16x32_bf16 v[24:27], v[92:95], v[172:175], v[24:27]
	v_mfma_f32_16x16x32_bf16 v[20:23], v[116:119], v[172:175], v[20:23]
	v_mfma_f32_16x16x32_bf16 v[8:11], v[92:95], v[188:191], v[8:11]
	v_mfma_f32_16x16x32_bf16 v[4:7], v[116:119], v[188:191], v[4:7]
	v_mfma_f32_16x16x32_bf16 v[56:59], v[92:95], v[152:155], v[60:63]
	v_mfma_f32_16x16x32_bf16 v[52:55], v[128:131], v[156:159], v[52:55]
	v_mfma_f32_16x16x32_bf16 v[40:43], v[104:107], v[164:167], v[40:43]
	v_mfma_f32_16x16x32_bf16 v[36:39], v[128:131], v[164:167], v[36:39]
	v_mfma_f32_16x16x32_bf16 v[24:27], v[104:107], v[184:187], v[24:27]
	v_mfma_f32_16x16x32_bf16 v[20:23], v[128:131], v[184:187], v[20:23]
	v_mfma_f32_16x16x32_bf16 v[8:11], v[104:107], v[192:195], v[8:11]
	v_mfma_f32_16x16x32_bf16 v[4:7], v[128:131], v[192:195], v[4:7]
	v_mfma_f32_16x16x32_bf16 v[56:59], v[104:107], v[156:159], v[56:59]
	s_barrier
; #define PG8_STAGE(bufoff, gbase, voff) do { _Pragma("unroll") for (int _i = 0; _i < 2; ++_i) \
;         __builtin_amdgcn_global_load_lds((const unsigned*)((const char*)(gbase) + (voff)[_i]), (PG8_LAS unsigned*)(lds + (bufoff) + ldsw + _i * 8192), 16, 0, 0); } while (0)
; #define PG8_LDA(dst, b, h) do { _Pragma("unroll") for (int m = 0; m < 4; ++m) _Pragma("unroll") for (int k = 0; k < 2; ++k) dst[m][k] = *(const PG8_LAS bf16x8*)(lds + PG8_SA(b, h) + aoff + m * 2048 + k * 1024); } while (0)
; #define PG8_LDB(dst, b, h) do { _Pragma("unroll") for (int n = 0; n < 2; ++n) _Pragma("unroll") for (int k = 0; k < 2; ++k) dst[n][k] = *(const PG8_LAS bf16x8*)(lds + PG8_SB(b, h) + boff + n * 2048 + k * 1024); } while (0)
; #define PG8_MMA(ai, bj, At, Bt) do { __builtin_amdgcn_s_setprio(1); _Pragma("unroll") for (int m = 0; m < 4; ++m) _Pragma("unroll") for (int n = 0; n < 2; ++n) _Pragma("unroll") for (int k = 0; k < 2; ++k) \
;         acc[ai][bj][m][n] = __builtin_amdgcn_mfma_f32_16x16x32_bf16(Bt[n][k], At[m][k], acc[ai][bj][m][n], 0, 0, 0); __builtin_amdgcn_s_setprio(0); } while (0)
; #define PG8_WAIT_V(n) asm volatile("s_waitcnt vmcnt(" #n ")" ::: "memory")
; #define PG8_WAIT_L(n) asm volatile("s_waitcnt lgkmcnt(" #n ")" ::: "memory")
; #define PG8_BAR __builtin_amdgcn_s_barrier()
; #define PG8_SCHED __builtin_amdgcn_sched_barrier(0)
; template <class Epi, class Sched, bool ALIGN_EPI = true>
; __device__ __forceinline__ void gemm_phase(PG8_LAS unsigned char* lds, const Gemm g, const Sched& S, const Epi& E, const int tid) {
;     ...
;             PG8_LDB(B0, 1, 0); PG8_LDB(B1, 1, 1); PG8_SCHED; PG8_LDA(At, 1, 0); PG8_STAGE(PG8_SA(0, 1), a2 + hstepA, voffA);
;             PG8_WAIT_V(8); PG8_WAIT_L(0); PG8_BAR; PG8_MMA(0, 0, At, B0); PG8_MMA(0, 1, At, B1); PG8_BAR; PG8_SCHED;
;             PG8_LDA(At, 1, 1); PG8_STAGE(PG8_SB(1, 0), b3, voffB); PG8_STAGE(PG8_SB(1, 1), b3 + hstepB, voffB); PG8_STAGE(PG8_SA(1, 0), a3, voffA);
;             PG8_WAIT_V(8); PG8_WAIT_L(0); PG8_BAR; PG8_MMA(1, 0, At, B0); PG8_MMA(1, 1, At, B1); PG8_BAR; PG8_SCHED;
;         }
;         if constexpr (ALIGN_EPI) { if (wr == 0) PG8_BAR; }
;         E(acc, cur, wr, wc, fr, fq); S.done(cur);
;         if (!has_next) break;
	s_add_i32 s15, 0, 0x18000
	s_add_i32 s16, 0, 0x1c000
	v_add_u32_e32 v72, s15, v251
	v_add_u32_e32 v128, s16, v251
	ds_read_b128 v[60:63], v72
	ds_read_b128 v[64:67], v72 offset:1024
	ds_read_b128 v[68:71], v72 offset:2048
	ds_read_b128 v[72:75], v72 offset:3072
	ds_read_b128 v[92:95], v128
	ds_read_b128 v[104:107], v128 offset:1024
	ds_read_b128 v[116:119], v128 offset:2048
	ds_read_b128 v[128:131], v128 offset:3072
	s_add_u32 s54, s54, 0x80000
	s_addc_u32 s55, s55, 0
	s_mov_b32 m0, s62
	ds_read_b128 v[152:155], v252 offset:32768
	ds_read_b128 v[156:159], v252 offset:33792
	ds_read_b128 v[160:163], v252 offset:34816
	ds_read_b128 v[172:175], v252 offset:35840
	ds_read_b128 v[184:187], v252 offset:36864
	ds_read_b128 v[188:191], v252 offset:37888
	ds_read_b128 v[192:195], v252 offset:38912
	ds_read_b128 v[196:199], v252 offset:39936
	global_load_lds_dwordx4 v210, s[54:55]
	s_mov_b32 m0, s63
	s_nop 0
	global_load_lds_dwordx4 v212, s[54:55]
	s_waitcnt vmcnt(8)
	s_waitcnt lgkmcnt(0)
	s_barrier
	s_waitcnt lgkmcnt(0)
	v_mfma_f32_16x16x32_bf16 v[164:167], v[60:63], v[152:155], v[180:183]
	v_mfma_f32_16x16x32_bf16 v[180:183], v[64:67], v[156:159], v[164:167]
	v_mfma_f32_16x16x32_bf16 v[164:167], v[68:71], v[152:155], v[176:179]
	v_mfma_f32_16x16x32_bf16 v[148:151], v[60:63], v[160:163], v[148:151]
	v_mfma_f32_16x16x32_bf16 v[144:147], v[68:71], v[160:163], v[144:147]
	v_mfma_f32_16x16x32_bf16 v[124:127], v[60:63], v[184:187], v[124:127]
	v_mfma_f32_16x16x32_bf16 v[120:123], v[68:71], v[184:187], v[120:123]
	v_mfma_f32_16x16x32_bf16 v[100:103], v[60:63], v[192:195], v[100:103]
	v_mfma_f32_16x16x32_bf16 v[96:99], v[68:71], v[192:195], v[96:99]
	v_mfma_f32_16x16x32_bf16 v[176:179], v[72:75], v[156:159], v[164:167]
	v_mfma_f32_16x16x32_bf16 v[148:151], v[64:67], v[172:175], v[148:151]
	v_mfma_f32_16x16x32_bf16 v[144:147], v[72:75], v[172:175], v[144:147]
	v_mfma_f32_16x16x32_bf16 v[124:127], v[64:67], v[188:191], v[124:127]
	v_mfma_f32_16x16x32_bf16 v[120:123], v[72:75], v[188:191], v[120:123]
	v_mfma_f32_16x16x32_bf16 v[100:103], v[64:67], v[196:199], v[100:103]
	v_mfma_f32_16x16x32_bf16 v[96:99], v[72:75], v[196:199], v[96:99]
	v_mfma_f32_16x16x32_bf16 v[164:167], v[92:95], v[152:155], v[168:171]
	v_mfma_f32_16x16x32_bf16 v[140:143], v[116:119], v[152:155], v[140:143]
	v_mfma_f32_16x16x32_bf16 v[136:139], v[92:95], v[160:163], v[136:139]
	v_mfma_f32_16x16x32_bf16 v[132:135], v[116:119], v[160:163], v[132:135]
	v_mfma_f32_16x16x32_bf16 v[112:115], v[92:95], v[184:187], v[112:115]
	v_mfma_f32_16x16x32_bf16 v[108:111], v[116:119], v[184:187], v[108:111]
	v_mfma_f32_16x16x32_bf16 v[88:91], v[92:95], v[192:195], v[88:91]
	v_mfma_f32_16x16x32_bf16 v[84:87], v[116:119], v[192:195], v[84:87]
	v_mfma_f32_16x16x32_bf16 v[168:171], v[104:107], v[156:159], v[164:167]
	v_mfma_f32_16x16x32_bf16 v[164:167], v[128:131], v[156:159], v[140:143]
	v_mfma_f32_16x16x32_bf16 v[136:139], v[104:107], v[172:175], v[136:139]
	v_mfma_f32_16x16x32_bf16 v[132:135], v[128:131], v[172:175], v[132:135]
	v_mfma_f32_16x16x32_bf16 v[112:115], v[104:107], v[188:191], v[112:115]
	v_mfma_f32_16x16x32_bf16 v[108:111], v[128:131], v[188:191], v[108:111]
	v_mfma_f32_16x16x32_bf16 v[88:91], v[104:107], v[196:199], v[88:91]
	v_mfma_f32_16x16x32_bf16 v[84:87], v[128:131], v[196:199], v[84:87]
	s_barrier
	s_add_i32 s15, s15, s60
	s_mov_b32 m0, s15
	ds_read_b128 v[140:143], v252 offset:49152
	ds_read_b128 v[152:155], v252 offset:50176
	ds_read_b128 v[156:159], v252 offset:51200
	ds_read_b128 v[160:163], v252 offset:52224
	ds_read_b128 v[172:175], v252 offset:53248
	ds_read_b128 v[184:187], v252 offset:54272
	ds_read_b128 v[188:191], v252 offset:55296
	ds_read_b128 v[192:195], v252 offset:56320
	s_add_u32 s98, s22, 0x80
	s_addc_u32 s99, s23, 0
	global_load_lds_dwordx4 v2, s[98:99]
	s_add_i32 m0, s15, 0x2000
	s_add_u32 s22, s22, 0x80080
	s_addc_u32 s23, s23, 0
	s_add_i32 s15, s16, s60
	global_load_lds_dwordx4 v214, s[98:99]
	s_mov_b32 m0, s15
	s_nop 0
	global_load_lds_dwordx4 v2, s[22:23]
	s_add_i32 m0, s15, 0x2000
	s_nop 0
	global_load_lds_dwordx4 v214, s[22:23]
	s_mov_b32 m0, s68
	s_nop 0
	s_add_u32 s98, s54, 0xfff80080
	s_addc_u32 s99, s55, -1
	global_load_lds_dwordx4 v210, s[98:99]
	s_mov_b32 m0, s69
	s_nop 0
	global_load_lds_dwordx4 v212, s[98:99]
	s_waitcnt vmcnt(8)
	s_waitcnt lgkmcnt(0)
	s_barrier
	s_waitcnt lgkmcnt(0)
	v_mfma_f32_16x16x32_bf16 v[80:83], v[60:63], v[140:143], v[80:83]
	v_mfma_f32_16x16x32_bf16 v[80:83], v[64:67], v[152:155], v[80:83]
	v_mfma_f32_16x16x32_bf16 v[76:79], v[72:75], v[152:155], v[76:79]
	v_mfma_f32_16x16x32_bf16 v[76:79], v[68:71], v[140:143], v[76:79]
	v_mfma_f32_16x16x32_bf16 v[44:47], v[68:71], v[156:159], v[44:47]
	v_mfma_f32_16x16x32_bf16 v[44:47], v[72:75], v[160:163], v[44:47]
	v_mfma_f32_16x16x32_bf16 v[48:51], v[64:67], v[160:163], v[48:51]
	v_mfma_f32_16x16x32_bf16 v[48:51], v[60:63], v[156:159], v[48:51]
	v_mfma_f32_16x16x32_bf16 v[32:35], v[60:63], v[172:175], v[32:35]
	v_mfma_f32_16x16x32_bf16 v[32:35], v[64:67], v[184:187], v[32:35]
	v_mfma_f32_16x16x32_bf16 v[28:31], v[72:75], v[184:187], v[28:31]
	v_mfma_f32_16x16x32_bf16 v[28:31], v[68:71], v[172:175], v[28:31]
	v_mfma_f32_16x16x32_bf16 v[12:15], v[68:71], v[188:191], v[12:15]
	v_mfma_f32_16x16x32_bf16 v[12:15], v[72:75], v[192:195], v[12:15]
	v_mfma_f32_16x16x32_bf16 v[16:19], v[64:67], v[192:195], v[16:19]
	v_mfma_f32_16x16x32_bf16 v[16:19], v[60:63], v[188:191], v[16:19]
	v_mfma_f32_16x16x32_bf16 v[56:59], v[92:95], v[140:143], v[56:59]
	v_mfma_f32_16x16x32_bf16 v[52:55], v[116:119], v[140:143], v[52:55]
	v_mfma_f32_16x16x32_bf16 v[40:43], v[92:95], v[156:159], v[40:43]
	v_mfma_f32_16x16x32_bf16 v[36:39], v[116:119], v[156:159], v[36:39]
	v_mfma_f32_16x16x32_bf16 v[24:27], v[92:95], v[172:175], v[24:27]
	v_mfma_f32_16x16x32_bf16 v[20:23], v[116:119], v[172:175], v[20:23]
	v_mfma_f32_16x16x32_bf16 v[8:11], v[92:95], v[188:191], v[8:11]
	v_mfma_f32_16x16x32_bf16 v[4:7], v[116:119], v[188:191], v[4:7]
	v_mfma_f32_16x16x32_bf16 v[60:63], v[104:107], v[152:155], v[56:59]
	v_mfma_f32_16x16x32_bf16 v[52:55], v[128:131], v[152:155], v[52:55]
	v_mfma_f32_16x16x32_bf16 v[40:43], v[104:107], v[160:163], v[40:43]
	v_mfma_f32_16x16x32_bf16 v[36:39], v[128:131], v[160:163], v[36:39]
	v_mfma_f32_16x16x32_bf16 v[24:27], v[104:107], v[184:187], v[24:27]
	v_mfma_f32_16x16x32_bf16 v[20:23], v[128:131], v[184:187], v[20:23]
	v_mfma_f32_16x16x32_bf16 v[8:11], v[104:107], v[192:195], v[8:11]
	v_mfma_f32_16x16x32_bf16 v[4:7], v[128:131], v[192:195], v[4:7]
	s_barrier
	s_add_u32 s12, s12, 0x100
	s_addc_u32 s13, s13, 0
	s_add_u32 s20, s20, 0x100
	s_addc_u32 s21, s21, 0
	s_cmp_ge_i32 s45, s9
	s_mov_b32 s22, s45
	s_cbranch_scc0 .LBB0_1087
	s_and_b64 vcc, exec, s[42:43]
	s_cbranch_vccz .LBB0_1090
	s_barrier

; #define PG8_STAGE(bufoff, gbase, voff) do { _Pragma("unroll") for (int _i = 0; _i < 2; ++_i) \
;         __builtin_amdgcn_global_load_lds((const unsigned*)((const char*)(gbase) + (voff)[_i]), (PG8_LAS unsigned*)(lds + (bufoff) + ldsw + _i * 8192), 16, 0, 0); } while (0)
; #define PG8_LDA(dst, b, h) do { _Pragma("unroll") for (int m = 0; m < 4; ++m) _Pragma("unroll") for (int k = 0; k < 2; ++k) dst[m][k] = *(const PG8_LAS bf16x8*)(lds + PG8_SA(b, h) + aoff + m * 2048 + k * 1024); } while (0)
; #define PG8_LDB(dst, b, h) do { _Pragma("unroll") for (int n = 0; n < 2; ++n) _Pragma("unroll") for (int k = 0; k < 2; ++k) dst[n][k] = *(const PG8_LAS bf16x8*)(lds + PG8_SB(b, h) + boff + n * 2048 + k * 1024); } while (0)
; template <class Epi, class Sched, bool ALIGN_EPI = true>
; __device__ __forceinline__ void gemm_phase(PG8_LAS unsigned char* lds, const Gemm g, const Sched& S, const Epi& E, const int tid) {
;     ...
;         for (int t = 0; t < nt; t += 2) {
;             const bool last = (t == nt - 2);
;             const char* a1 = cA + (size_t)(t + 1) * kstep;
;             const char* a2 = last ? nA : cA + (size_t)(t + 2) * kstep; const char* b2 = last ? nB : cB + (size_t)(t + 2) * kstep;
;             const char* a3 = a2 + kstep; const char* b3 = b2 + kstep;
;             if (last && has_next) S.a_ready(nxt);
;             PG8_LDB(B0, 0, 0); PG8_LDB(B1, 0, 1); PG8_SCHED; PG8_LDA(At, 0, 0); PG8_STAGE(PG8_SA(1, 1), a1 + hstepA, voffA);
;             PG8_WAIT_V(8); PG8_WAIT_L(0); PG8_BAR; PG8_MMA(0, 0, At, B0); PG8_MMA(0, 1, At, B1); PG8_BAR; PG8_SCHED;
;             PG8_LDA(At, 0, 1); PG8_STAGE(PG8_SB(0, 0), b2, voffB); PG8_STAGE(PG8_SB(0, 1), b2 + hstepB, voffB); PG8_STAGE(PG8_SA(0, 0), a2, voffA);
;             PG8_WAIT_V(8); PG8_WAIT_L(0); PG8_BAR; PG8_MMA(1, 0, At, B0); PG8_MMA(1, 1, At, B1); PG8_BAR; PG8_SCHED;
;             PG8_LDB(B0, 1, 0); PG8_LDB(B1, 1, 1); PG8_SCHED; PG8_LDA(At, 1, 0); PG8_STAGE(PG8_SA(0, 1), a2 + hstepA, voffA);
;             PG8_WAIT_V(8); PG8_WAIT_L(0); PG8_BAR; PG8_MMA(0, 0, At, B0); PG8_MMA(0, 1, At, B1); PG8_BAR; PG8_SCHED;
;             PG8_LDA(At, 1, 1); PG8_STAGE(PG8_SB(1, 0), b3, voffB); PG8_STAGE(PG8_SB(1, 1), b3 + hstepB, voffB); PG8_STAGE(PG8_SA(1, 0), a3, voffA);
;             PG8_WAIT_V(8); PG8_WAIT_L(0); PG8_BAR; PG8_MMA(1, 0, At, B0); PG8_MMA(1, 1, At, B1); PG8_BAR; PG8_SCHED;
.LBB0_1238:
	s_add_u32 s15, s74, 0xfff80080
	s_addc_u32 s16, s75, -1
	s_add_i32 s17, 0, 0x10000
	s_cmp_eq_u32 s21, 28
	s_cselect_b32 s79, s8, s16
	s_cselect_b32 s78, s11, s15
	s_cselect_b32 s77, s13, s20
	s_cselect_b32 s76, s18, s19
	s_add_i32 s15, 0, 0x14000
	v_add_u32_e32 v88, s17, v193
	v_add_u32_e32 v104, s15, v193
	ds_read_b128 v[72:75], v88
	ds_read_b128 v[76:79], v88 offset:1024
	ds_read_b128 v[84:87], v88 offset:2048
	ds_read_b128 v[88:91], v88 offset:3072
	ds_read_b128 v[92:95], v104
	ds_read_b128 v[96:99], v104 offset:1024
	ds_read_b128 v[100:103], v104 offset:2048
	ds_read_b128 v[104:107], v104 offset:3072
	s_add_i32 m0, s86, 0xc000
	ds_read_b128 v[164:167], v200
	ds_read_b128 v[168:171], v200 offset:1024
	ds_read_b128 v[172:175], v200 offset:2048
	ds_read_b128 v[176:179], v200 offset:3072
	ds_read_b128 v[202:205], v200 offset:4096
	ds_read_b128 v[210:213], v200 offset:5120
	ds_read_b128 v[214:217], v200 offset:6144
	ds_read_b128 v[218:221], v200 offset:7168
	global_load_lds_dwordx4 v186, s[74:75]
	s_add_i32 m0, s86, 0xe000
	s_nop 0
	global_load_lds_dwordx4 v188, s[74:75]
	s_waitcnt vmcnt(8)
	s_waitcnt lgkmcnt(0)
	s_barrier
	s_waitcnt lgkmcnt(0)
	v_mfma_f32_16x16x32_bf16 v[160:163], v[72:75], v[164:167], v[160:163]
	v_mfma_f32_16x16x32_bf16 v[160:163], v[76:79], v[168:171], v[160:163]
	v_mfma_f32_16x16x32_bf16 v[156:159], v[88:91], v[168:171], v[156:159]
	v_mfma_f32_16x16x32_bf16 v[156:159], v[84:87], v[164:167], v[156:159]
	v_mfma_f32_16x16x32_bf16 v[140:143], v[84:87], v[172:175], v[140:143]
	v_mfma_f32_16x16x32_bf16 v[140:143], v[88:91], v[176:179], v[140:143]
	v_mfma_f32_16x16x32_bf16 v[144:147], v[76:79], v[176:179], v[144:147]
	v_mfma_f32_16x16x32_bf16 v[144:147], v[72:75], v[172:175], v[144:147]
	v_mfma_f32_16x16x32_bf16 v[128:131], v[72:75], v[202:205], v[128:131]
	v_mfma_f32_16x16x32_bf16 v[128:131], v[76:79], v[210:213], v[128:131]
	v_mfma_f32_16x16x32_bf16 v[124:127], v[88:91], v[210:213], v[124:127]
	v_mfma_f32_16x16x32_bf16 v[124:127], v[84:87], v[202:205], v[124:127]
	v_mfma_f32_16x16x32_bf16 v[68:71], v[84:87], v[214:217], v[68:71]
	v_mfma_f32_16x16x32_bf16 v[68:71], v[88:91], v[218:221], v[68:71]
	v_mfma_f32_16x16x32_bf16 v[80:83], v[76:79], v[218:221], v[80:83]
	v_mfma_f32_16x16x32_bf16 v[80:83], v[72:75], v[214:217], v[80:83]
	v_mfma_f32_16x16x32_bf16 v[152:155], v[92:95], v[164:167], v[152:155]
	v_mfma_f32_16x16x32_bf16 v[152:155], v[96:99], v[168:171], v[152:155]
	v_mfma_f32_16x16x32_bf16 v[148:151], v[104:107], v[168:171], v[148:151]
	v_mfma_f32_16x16x32_bf16 v[148:151], v[100:103], v[164:167], v[148:151]
	v_mfma_f32_16x16x32_bf16 v[132:135], v[100:103], v[172:175], v[132:135]
	v_mfma_f32_16x16x32_bf16 v[132:135], v[104:107], v[176:179], v[132:135]
	v_mfma_f32_16x16x32_bf16 v[136:139], v[96:99], v[176:179], v[136:139]
	v_mfma_f32_16x16x32_bf16 v[136:139], v[92:95], v[172:175], v[136:139]
	v_mfma_f32_16x16x32_bf16 v[120:123], v[92:95], v[202:205], v[120:123]
	v_mfma_f32_16x16x32_bf16 v[120:123], v[96:99], v[210:213], v[120:123]
	v_mfma_f32_16x16x32_bf16 v[116:119], v[104:107], v[210:213], v[116:119]
	v_mfma_f32_16x16x32_bf16 v[116:119], v[100:103], v[202:205], v[116:119]
	v_mfma_f32_16x16x32_bf16 v[108:111], v[100:103], v[214:217], v[108:111]
	v_mfma_f32_16x16x32_bf16 v[108:111], v[104:107], v[218:221], v[108:111]
	v_mfma_f32_16x16x32_bf16 v[112:115], v[96:99], v[218:221], v[112:115]
	v_mfma_f32_16x16x32_bf16 v[112:115], v[92:95], v[214:217], v[112:115]
	s_barrier
	s_add_i32 s16, s17, s85
	s_mov_b32 m0, s16
	ds_read_b128 v[164:167], v200 offset:16384
	ds_read_b128 v[168:171], v200 offset:17408
	ds_read_b128 v[172:175], v200 offset:18432
	ds_read_b128 v[176:179], v200 offset:19456
	ds_read_b128 v[202:205], v200 offset:20480
	ds_read_b128 v[210:213], v200 offset:21504
	ds_read_b128 v[214:217], v200 offset:22528
	ds_read_b128 v[218:221], v200 offset:23552
	global_load_lds_dwordx4 v2, s[76:77]
	s_add_i32 m0, s16, 0x2000
	s_add_u32 s96, s76, 0x80000
	s_addc_u32 s97, s77, 0
	s_add_i32 s15, s15, s85
	global_load_lds_dwordx4 v184, s[76:77]
	s_mov_b32 m0, s15
	s_nop 0
	global_load_lds_dwordx4 v2, s[96:97]
	s_add_i32 m0, s15, 0x2000
	s_nop 0
	global_load_lds_dwordx4 v184, s[96:97]
	s_mov_b32 m0, s86
	s_nop 0
	global_load_lds_dwordx4 v180, s[78:79]
	s_mov_b32 m0, s87
	s_nop 0
	global_load_lds_dwordx4 v182, s[78:79]
	s_waitcnt vmcnt(8)
	s_waitcnt lgkmcnt(0)
	s_barrier
	s_waitcnt lgkmcnt(0)
	v_mfma_f32_16x16x32_bf16 v[64:67], v[72:75], v[164:167], v[64:67]
	v_mfma_f32_16x16x32_bf16 v[64:67], v[76:79], v[168:171], v[64:67]
	v_mfma_f32_16x16x32_bf16 v[60:63], v[88:91], v[168:171], v[60:63]
	v_mfma_f32_16x16x32_bf16 v[60:63], v[84:87], v[164:167], v[60:63]
	v_mfma_f32_16x16x32_bf16 v[44:47], v[84:87], v[172:175], v[44:47]
	v_mfma_f32_16x16x32_bf16 v[44:47], v[88:91], v[176:179], v[44:47]
	v_mfma_f32_16x16x32_bf16 v[48:51], v[76:79], v[176:179], v[48:51]
	v_mfma_f32_16x16x32_bf16 v[48:51], v[72:75], v[172:175], v[48:51]
	v_mfma_f32_16x16x32_bf16 v[32:35], v[72:75], v[202:205], v[32:35]
	v_mfma_f32_16x16x32_bf16 v[32:35], v[76:79], v[210:213], v[32:35]
	v_mfma_f32_16x16x32_bf16 v[28:31], v[88:91], v[210:213], v[28:31]
	v_mfma_f32_16x16x32_bf16 v[28:31], v[84:87], v[202:205], v[28:31]
	v_mfma_f32_16x16x32_bf16 v[4:7], v[84:87], v[214:217], v[4:7]
	v_mfma_f32_16x16x32_bf16 v[4:7], v[88:91], v[218:221], v[4:7]
	v_mfma_f32_16x16x32_bf16 v[8:11], v[76:79], v[218:221], v[8:11]
	v_mfma_f32_16x16x32_bf16 v[8:11], v[72:75], v[214:217], v[8:11]
	v_mfma_f32_16x16x32_bf16 v[56:59], v[92:95], v[164:167], v[56:59]
	v_mfma_f32_16x16x32_bf16 v[56:59], v[96:99], v[168:171], v[56:59]
	v_mfma_f32_16x16x32_bf16 v[52:55], v[104:107], v[168:171], v[52:55]
	v_mfma_f32_16x16x32_bf16 v[52:55], v[100:103], v[164:167], v[52:55]
	v_mfma_f32_16x16x32_bf16 v[36:39], v[100:103], v[172:175], v[36:39]
	v_mfma_f32_16x16x32_bf16 v[36:39], v[104:107], v[176:179], v[36:39]
	v_mfma_f32_16x16x32_bf16 v[40:43], v[96:99], v[176:179], v[40:43]
	v_mfma_f32_16x16x32_bf16 v[40:43], v[92:95], v[172:175], v[40:43]
	v_mfma_f32_16x16x32_bf16 v[24:27], v[92:95], v[202:205], v[24:27]
	v_mfma_f32_16x16x32_bf16 v[24:27], v[96:99], v[210:213], v[24:27]
	v_mfma_f32_16x16x32_bf16 v[20:23], v[104:107], v[210:213], v[20:23]
	v_mfma_f32_16x16x32_bf16 v[20:23], v[100:103], v[202:205], v[20:23]
	v_mfma_f32_16x16x32_bf16 v[12:15], v[100:103], v[214:217], v[12:15]
	v_mfma_f32_16x16x32_bf16 v[12:15], v[104:107], v[218:221], v[12:15]
	v_mfma_f32_16x16x32_bf16 v[16:19], v[96:99], v[218:221], v[16:19]
	v_mfma_f32_16x16x32_bf16 v[16:19], v[92:95], v[214:217], v[16:19]
	s_barrier
; #define PG8_STAGE(bufoff, gbase, voff) do { _Pragma("unroll") for (int _i = 0; _i < 2; ++_i) \
;         __builtin_amdgcn_global_load_lds((const unsigned*)((const char*)(gbase) + (voff)[_i]), (PG8_LAS unsigned*)(lds + (bufoff) + ldsw + _i * 8192), 16, 0, 0); } while (0)
; #define PG8_LDA(dst, b, h) do { _Pragma("unroll") for (int m = 0; m < 4; ++m) _Pragma("unroll") for (int k = 0; k < 2; ++k) dst[m][k] = *(const PG8_LAS bf16x8*)(lds + PG8_SA(b, h) + aoff + m * 2048 + k * 1024); } while (0)
; #define PG8_LDB(dst, b, h) do { _Pragma("unroll") for (int n = 0; n < 2; ++n) _Pragma("unroll") for (int k = 0; k < 2; ++k) dst[n][k] = *(const PG8_LAS bf16x8*)(lds + PG8_SB(b, h) + boff + n * 2048 + k * 1024); } while (0)
; #define PG8_MMA(ai, bj, At, Bt) do { __builtin_amdgcn_s_setprio(1); _Pragma("unroll") for (int m = 0; m < 4; ++m) _Pragma("unroll") for (int n = 0; n < 2; ++n) _Pragma("unroll") for (int k = 0; k < 2; ++k) \
;         acc[ai][bj][m][n] = __builtin_amdgcn_mfma_f32_16x16x32_bf16(Bt[n][k], At[m][k], acc[ai][bj][m][n], 0, 0, 0); __builtin_amdgcn_s_setprio(0); } while (0)
; #define PG8_WAIT_V(n) asm volatile("s_waitcnt vmcnt(" #n ")" ::: "memory")
; #define PG8_WAIT_L(n) asm volatile("s_waitcnt lgkmcnt(" #n ")" ::: "memory")
; #define PG8_BAR __builtin_amdgcn_s_barrier()
; #define PG8_SCHED __builtin_amdgcn_sched_barrier(0)
; template <class Epi, class Sched, bool ALIGN_EPI = true>
; __device__ __forceinline__ void gemm_phase(PG8_LAS unsigned char* lds, const Gemm g, const Sched& S, const Epi& E, const int tid) {
;     ...
;             PG8_LDB(B0, 1, 0); PG8_LDB(B1, 1, 1); PG8_SCHED; PG8_LDA(At, 1, 0); PG8_STAGE(PG8_SA(0, 1), a2 + hstepA, voffA);
;             PG8_WAIT_V(8); PG8_WAIT_L(0); PG8_BAR; PG8_MMA(0, 0, At, B0); PG8_MMA(0, 1, At, B1); PG8_BAR; PG8_SCHED;
;             PG8_LDA(At, 1, 1); PG8_STAGE(PG8_SB(1, 0), b3, voffB); PG8_STAGE(PG8_SB(1, 1), b3 + hstepB, voffB); PG8_STAGE(PG8_SA(1, 0), a3, voffA);
;             PG8_WAIT_V(8); PG8_WAIT_L(0); PG8_BAR; PG8_MMA(1, 0, At, B0); PG8_MMA(1, 1, At, B1); PG8_BAR; PG8_SCHED;
;         }
;         if constexpr (ALIGN_EPI) { if (wr == 0) PG8_BAR; }
;         E(acc, cur, wr, wc, fr, fq); S.done(cur);
;         if (!has_next) break;
	s_add_i32 s15, 0, 0x18000
	s_add_i32 s16, 0, 0x1c000
	v_add_u32_e32 v88, s15, v193
	v_add_u32_e32 v104, s16, v193
	ds_read_b128 v[72:75], v88
	ds_read_b128 v[76:79], v88 offset:1024
	ds_read_b128 v[84:87], v88 offset:2048
	ds_read_b128 v[88:91], v88 offset:3072
	ds_read_b128 v[92:95], v104
	ds_read_b128 v[96:99], v104 offset:1024
	ds_read_b128 v[100:103], v104 offset:2048
	ds_read_b128 v[104:107], v104 offset:3072
	s_add_u32 s78, s78, 0x80000
	s_addc_u32 s79, s79, 0
	s_mov_b32 m0, s88
	ds_read_b128 v[164:167], v200 offset:32768
	ds_read_b128 v[168:171], v200 offset:33792
	ds_read_b128 v[172:175], v200 offset:34816
	ds_read_b128 v[176:179], v200 offset:35840
	ds_read_b128 v[202:205], v200 offset:36864
	ds_read_b128 v[210:213], v200 offset:37888
	ds_read_b128 v[214:217], v200 offset:38912
	ds_read_b128 v[218:221], v200 offset:39936
	global_load_lds_dwordx4 v180, s[78:79]
	s_mov_b32 m0, s89
	s_nop 0
	global_load_lds_dwordx4 v182, s[78:79]
	s_waitcnt vmcnt(8)
	s_waitcnt lgkmcnt(0)
	s_barrier
	s_waitcnt lgkmcnt(0)
	v_mfma_f32_16x16x32_bf16 v[160:163], v[72:75], v[164:167], v[160:163]
	v_mfma_f32_16x16x32_bf16 v[160:163], v[76:79], v[168:171], v[160:163]
	v_mfma_f32_16x16x32_bf16 v[156:159], v[88:91], v[168:171], v[156:159]
	v_mfma_f32_16x16x32_bf16 v[156:159], v[84:87], v[164:167], v[156:159]
	v_mfma_f32_16x16x32_bf16 v[140:143], v[84:87], v[172:175], v[140:143]
	v_mfma_f32_16x16x32_bf16 v[140:143], v[88:91], v[176:179], v[140:143]
	v_mfma_f32_16x16x32_bf16 v[144:147], v[76:79], v[176:179], v[144:147]
	v_mfma_f32_16x16x32_bf16 v[144:147], v[72:75], v[172:175], v[144:147]
	v_mfma_f32_16x16x32_bf16 v[128:131], v[72:75], v[202:205], v[128:131]
	v_mfma_f32_16x16x32_bf16 v[128:131], v[76:79], v[210:213], v[128:131]
	v_mfma_f32_16x16x32_bf16 v[124:127], v[88:91], v[210:213], v[124:127]
	v_mfma_f32_16x16x32_bf16 v[124:127], v[84:87], v[202:205], v[124:127]
	v_mfma_f32_16x16x32_bf16 v[68:71], v[84:87], v[214:217], v[68:71]
	v_mfma_f32_16x16x32_bf16 v[68:71], v[88:91], v[218:221], v[68:71]
	v_mfma_f32_16x16x32_bf16 v[80:83], v[76:79], v[218:221], v[80:83]
	v_mfma_f32_16x16x32_bf16 v[80:83], v[72:75], v[214:217], v[80:83]
	v_mfma_f32_16x16x32_bf16 v[152:155], v[92:95], v[164:167], v[152:155]
	v_mfma_f32_16x16x32_bf16 v[152:155], v[96:99], v[168:171], v[152:155]
	v_mfma_f32_16x16x32_bf16 v[148:151], v[104:107], v[168:171], v[148:151]
	v_mfma_f32_16x16x32_bf16 v[148:151], v[100:103], v[164:167], v[148:151]
	v_mfma_f32_16x16x32_bf16 v[132:135], v[100:103], v[172:175], v[132:135]
	v_mfma_f32_16x16x32_bf16 v[132:135], v[104:107], v[176:179], v[132:135]
	v_mfma_f32_16x16x32_bf16 v[136:139], v[96:99], v[176:179], v[136:139]
	v_mfma_f32_16x16x32_bf16 v[136:139], v[92:95], v[172:175], v[136:139]
	v_mfma_f32_16x16x32_bf16 v[120:123], v[92:95], v[202:205], v[120:123]
	v_mfma_f32_16x16x32_bf16 v[120:123], v[96:99], v[210:213], v[120:123]
	v_mfma_f32_16x16x32_bf16 v[116:119], v[104:107], v[210:213], v[116:119]
	v_mfma_f32_16x16x32_bf16 v[116:119], v[100:103], v[202:205], v[116:119]
	v_mfma_f32_16x16x32_bf16 v[108:111], v[100:103], v[214:217], v[108:111]
	v_mfma_f32_16x16x32_bf16 v[108:111], v[104:107], v[218:221], v[108:111]
	v_mfma_f32_16x16x32_bf16 v[112:115], v[96:99], v[218:221], v[112:115]
	v_mfma_f32_16x16x32_bf16 v[112:115], v[92:95], v[214:217], v[112:115]
	s_barrier
	s_add_i32 s15, s15, s85
	s_mov_b32 m0, s15
	ds_read_b128 v[164:167], v200 offset:49152
	ds_read_b128 v[168:171], v200 offset:50176
	ds_read_b128 v[172:175], v200 offset:51200
	ds_read_b128 v[176:179], v200 offset:52224
	ds_read_b128 v[202:205], v200 offset:53248
	ds_read_b128 v[210:213], v200 offset:54272
	ds_read_b128 v[214:217], v200 offset:55296
	ds_read_b128 v[218:221], v200 offset:56320
	s_add_u32 s98, s76, 0x80
	s_addc_u32 s99, s77, 0
	global_load_lds_dwordx4 v2, s[98:99]
	s_add_i32 m0, s15, 0x2000
	s_add_u32 s76, s76, 0x80080
	s_addc_u32 s77, s77, 0
	s_add_i32 s15, s16, s85
	global_load_lds_dwordx4 v184, s[98:99]
	s_mov_b32 m0, s15
	s_nop 0
	global_load_lds_dwordx4 v2, s[76:77]
	s_add_i32 m0, s15, 0x2000
	s_nop 0
	global_load_lds_dwordx4 v184, s[76:77]
	s_mov_b32 m0, s92
	s_nop 0
	s_add_u32 s98, s78, 0xfff80080
	s_addc_u32 s99, s79, -1
	global_load_lds_dwordx4 v180, s[98:99]
	s_mov_b32 m0, s93
	s_nop 0
	global_load_lds_dwordx4 v182, s[98:99]
	s_waitcnt vmcnt(8)
	s_waitcnt lgkmcnt(0)
	s_barrier
	s_waitcnt lgkmcnt(0)
	v_mfma_f32_16x16x32_bf16 v[64:67], v[72:75], v[164:167], v[64:67]
	v_mfma_f32_16x16x32_bf16 v[64:67], v[76:79], v[168:171], v[64:67]
	v_mfma_f32_16x16x32_bf16 v[60:63], v[88:91], v[168:171], v[60:63]
	v_mfma_f32_16x16x32_bf16 v[60:63], v[84:87], v[164:167], v[60:63]
	v_mfma_f32_16x16x32_bf16 v[44:47], v[84:87], v[172:175], v[44:47]
	v_mfma_f32_16x16x32_bf16 v[44:47], v[88:91], v[176:179], v[44:47]
	v_mfma_f32_16x16x32_bf16 v[48:51], v[76:79], v[176:179], v[48:51]
	v_mfma_f32_16x16x32_bf16 v[48:51], v[72:75], v[172:175], v[48:51]
	v_mfma_f32_16x16x32_bf16 v[32:35], v[72:75], v[202:205], v[32:35]
	v_mfma_f32_16x16x32_bf16 v[32:35], v[76:79], v[210:213], v[32:35]
	v_mfma_f32_16x16x32_bf16 v[28:31], v[88:91], v[210:213], v[28:31]
	v_mfma_f32_16x16x32_bf16 v[28:31], v[84:87], v[202:205], v[28:31]
	v_mfma_f32_16x16x32_bf16 v[4:7], v[84:87], v[214:217], v[4:7]
	v_mfma_f32_16x16x32_bf16 v[4:7], v[88:91], v[218:221], v[4:7]
	v_mfma_f32_16x16x32_bf16 v[8:11], v[76:79], v[218:221], v[8:11]
	v_mfma_f32_16x16x32_bf16 v[8:11], v[72:75], v[214:217], v[8:11]
	v_mfma_f32_16x16x32_bf16 v[56:59], v[92:95], v[164:167], v[56:59]
	v_mfma_f32_16x16x32_bf16 v[56:59], v[96:99], v[168:171], v[56:59]
	v_mfma_f32_16x16x32_bf16 v[52:55], v[104:107], v[168:171], v[52:55]
	v_mfma_f32_16x16x32_bf16 v[52:55], v[100:103], v[164:167], v[52:55]
	v_mfma_f32_16x16x32_bf16 v[36:39], v[100:103], v[172:175], v[36:39]
	v_mfma_f32_16x16x32_bf16 v[36:39], v[104:107], v[176:179], v[36:39]
	v_mfma_f32_16x16x32_bf16 v[40:43], v[96:99], v[176:179], v[40:43]
	v_mfma_f32_16x16x32_bf16 v[40:43], v[92:95], v[172:175], v[40:43]
	v_mfma_f32_16x16x32_bf16 v[24:27], v[92:95], v[202:205], v[24:27]
	v_mfma_f32_16x16x32_bf16 v[24:27], v[96:99], v[210:213], v[24:27]
	v_mfma_f32_16x16x32_bf16 v[20:23], v[104:107], v[210:213], v[20:23]
	v_mfma_f32_16x16x32_bf16 v[20:23], v[100:103], v[202:205], v[20:23]
	v_mfma_f32_16x16x32_bf16 v[12:15], v[100:103], v[214:217], v[12:15]
	v_mfma_f32_16x16x32_bf16 v[12:15], v[104:107], v[218:221], v[12:15]
	v_mfma_f32_16x16x32_bf16 v[16:19], v[96:99], v[218:221], v[16:19]
	v_mfma_f32_16x16x32_bf16 v[16:19], v[92:95], v[214:217], v[16:19]
	s_barrier
	s_add_i32 s21, s21, 2
	s_add_u32 s74, s74, 0x100
	s_addc_u32 s75, s75, 0
	s_add_u32 s19, s19, 0x100
	s_addc_u32 s20, s20, 0
	s_cmp_gt_u32 s21, 29
	s_cbranch_scc0 .LBB0_1238
	s_and_b64 vcc, exec, s[56:57]
	s_cbranch_vccnz .LBB0_1264
	s_and_saveexec_b64 s[18:19], s[38:39]
	s_cbranch_execnz .LBB0_1265

; #define PG8_STAGE(bufoff, gbase, voff) do { _Pragma("unroll") for (int _i = 0; _i < 2; ++_i) \
;         __builtin_amdgcn_global_load_lds((const unsigned*)((const char*)(gbase) + (voff)[_i]), (PG8_LAS unsigned*)(lds + (bufoff) + ldsw + _i * 8192), 16, 0, 0); } while (0)
; #define PG8_LDA(dst, b, h) do { _Pragma("unroll") for (int m = 0; m < 4; ++m) _Pragma("unroll") for (int k = 0; k < 2; ++k) dst[m][k] = *(const PG8_LAS bf16x8*)(lds + PG8_SA(b, h) + aoff + m * 2048 + k * 1024); } while (0)
; #define PG8_LDB(dst, b, h) do { _Pragma("unroll") for (int n = 0; n < 2; ++n) _Pragma("unroll") for (int k = 0; k < 2; ++k) dst[n][k] = *(const PG8_LAS bf16x8*)(lds + PG8_SB(b, h) + boff + n * 2048 + k * 1024); } while (0)
; #define PG8_MMA(ai, bj, At, Bt) do { __builtin_amdgcn_s_setprio(1); _Pragma("unroll") for (int m = 0; m < 4; ++m) _Pragma("unroll") for (int n = 0; n < 2; ++n) _Pragma("unroll") for (int k = 0; k < 2; ++k) \
;         acc[ai][bj][m][n] = __builtin_amdgcn_mfma_f32_16x16x32_bf16(Bt[n][k], At[m][k], acc[ai][bj][m][n], 0, 0, 0); __builtin_amdgcn_s_setprio(0); } while (0)
; #define PG8_WAIT_V(n) asm volatile("s_waitcnt vmcnt(" #n ")" ::: "memory")
; #define PG8_WAIT_L(n) asm volatile("s_waitcnt lgkmcnt(" #n ")" ::: "memory")
; template <class Epi, class Sched, bool ALIGN_EPI = true>
; __device__ __forceinline__ void gemm_phase(PG8_LAS unsigned char* lds, const Gemm g, const Sched& S, const Epi& E, const int tid) {
;     ...
;         for (int t = 0; t < nt; t += 2) {
;             const bool last = (t == nt - 2);
;             const char* a1 = cA + (size_t)(t + 1) * kstep;
;             const char* a2 = last ? nA : cA + (size_t)(t + 2) * kstep; const char* b2 = last ? nB : cB + (size_t)(t + 2) * kstep;
;             const char* a3 = a2 + kstep; const char* b3 = b2 + kstep;
;             if (last && has_next) S.a_ready(nxt);
;             PG8_LDB(B0, 0, 0); PG8_LDB(B1, 0, 1); PG8_SCHED; PG8_LDA(At, 0, 0); PG8_STAGE(PG8_SA(1, 1), a1 + hstepA, voffA);
;             PG8_WAIT_V(8); PG8_WAIT_L(0); PG8_BAR; PG8_MMA(0, 0, At, B0); PG8_MMA(0, 1, At, B1); PG8_BAR; PG8_SCHED;
;             PG8_LDA(At, 0, 1); PG8_STAGE(PG8_SB(0, 0), b2, voffB); PG8_STAGE(PG8_SB(0, 1), b2 + hstepB, voffB); PG8_STAGE(PG8_SA(0, 0), a2, voffA);
;             PG8_WAIT_V(8); PG8_WAIT_L(0); PG8_BAR; PG8_MMA(1, 0, At, B0); PG8_MMA(1, 1, At, B1); PG8_BAR; PG8_SCHED;
.LBB0_1414:
	s_add_i32 s70, s12, 2
	s_add_u32 s10, s0, 0x100
	s_addc_u32 s11, s1, 0
	s_add_i32 s15, 0, 0x10000
	s_cmp_eq_u32 s45, s12
	s_cselect_b32 s23, s47, s11
	s_cselect_b32 s22, s46, s10
	s_cselect_b32 s13, s49, s69
	s_cselect_b32 s12, s48, s68
	s_add_i32 s16, 0, 0x14000
	v_add_u32_e32 v72, s15, v251
	v_add_u32_e32 v128, s16, v251
	ds_read_b128 v[56:59], v72
	ds_read_b128 v[60:63], v72 offset:1024
	ds_read_b128 v[68:71], v72 offset:2048
	ds_read_b128 v[72:75], v72 offset:3072
	ds_read_b128 v[92:95], v128
	ds_read_b128 v[104:107], v128 offset:1024
	ds_read_b128 v[116:119], v128 offset:2048
	ds_read_b128 v[128:131], v128 offset:3072
	s_add_i32 m0, s52, 0xc000
	ds_read_b128 v[140:143], v252
	ds_read_b128 v[152:155], v252 offset:1024
	ds_read_b128 v[156:159], v252 offset:2048
	ds_read_b128 v[160:163], v252 offset:3072
	ds_read_b128 v[172:175], v252 offset:4096
	ds_read_b128 v[184:187], v252 offset:5120
	ds_read_b128 v[188:191], v252 offset:6144
	ds_read_b128 v[192:195], v252 offset:7168
	global_load_lds_dwordx4 v216, s[0:1]
	s_add_i32 m0, s52, 0xe000
	s_nop 0
	global_load_lds_dwordx4 v218, s[0:1]
	s_waitcnt vmcnt(8)
	s_waitcnt lgkmcnt(0)
	s_barrier
	s_waitcnt lgkmcnt(0)
	v_mfma_f32_16x16x32_bf16 v[180:183], v[56:59], v[140:143], v[180:183]
	v_mfma_f32_16x16x32_bf16 v[180:183], v[60:63], v[152:155], v[180:183]
	v_mfma_f32_16x16x32_bf16 v[176:179], v[72:75], v[152:155], v[176:179]
	v_mfma_f32_16x16x32_bf16 v[176:179], v[68:71], v[140:143], v[176:179]
	v_mfma_f32_16x16x32_bf16 v[144:147], v[68:71], v[156:159], v[144:147]
	v_mfma_f32_16x16x32_bf16 v[144:147], v[72:75], v[160:163], v[144:147]
	v_mfma_f32_16x16x32_bf16 v[148:151], v[60:63], v[160:163], v[148:151]
	v_mfma_f32_16x16x32_bf16 v[148:151], v[56:59], v[156:159], v[148:151]
	v_mfma_f32_16x16x32_bf16 v[124:127], v[56:59], v[172:175], v[124:127]
	v_mfma_f32_16x16x32_bf16 v[124:127], v[60:63], v[184:187], v[124:127]
	v_mfma_f32_16x16x32_bf16 v[120:123], v[72:75], v[184:187], v[120:123]
	v_mfma_f32_16x16x32_bf16 v[120:123], v[68:71], v[172:175], v[120:123]
	v_mfma_f32_16x16x32_bf16 v[96:99], v[68:71], v[188:191], v[96:99]
	v_mfma_f32_16x16x32_bf16 v[96:99], v[72:75], v[192:195], v[96:99]
	v_mfma_f32_16x16x32_bf16 v[100:103], v[60:63], v[192:195], v[100:103]
	v_mfma_f32_16x16x32_bf16 v[100:103], v[56:59], v[188:191], v[100:103]
	v_mfma_f32_16x16x32_bf16 v[168:171], v[92:95], v[140:143], v[168:171]
	v_mfma_f32_16x16x32_bf16 v[136:139], v[92:95], v[156:159], v[136:139]
	v_mfma_f32_16x16x32_bf16 v[132:135], v[116:119], v[156:159], v[132:135]
	v_mfma_f32_16x16x32_bf16 v[112:115], v[92:95], v[172:175], v[112:115]
	v_mfma_f32_16x16x32_bf16 v[108:111], v[116:119], v[172:175], v[108:111]
	v_mfma_f32_16x16x32_bf16 v[88:91], v[92:95], v[188:191], v[88:91]
	v_mfma_f32_16x16x32_bf16 v[84:87], v[116:119], v[188:191], v[84:87]
	v_mfma_f32_16x16x32_bf16 v[168:171], v[104:107], v[152:155], v[168:171]
	v_mfma_f32_16x16x32_bf16 v[140:143], v[116:119], v[140:143], v[164:167]
	v_mfma_f32_16x16x32_bf16 v[136:139], v[104:107], v[160:163], v[136:139]
	v_mfma_f32_16x16x32_bf16 v[132:135], v[128:131], v[160:163], v[132:135]
	v_mfma_f32_16x16x32_bf16 v[112:115], v[104:107], v[184:187], v[112:115]
	v_mfma_f32_16x16x32_bf16 v[108:111], v[128:131], v[184:187], v[108:111]
	v_mfma_f32_16x16x32_bf16 v[88:91], v[104:107], v[192:195], v[88:91]
	v_mfma_f32_16x16x32_bf16 v[84:87], v[128:131], v[192:195], v[84:87]
	v_mfma_f32_16x16x32_bf16 v[140:143], v[128:131], v[152:155], v[140:143]
	s_barrier
	s_add_i32 s0, s15, s51
	s_mov_b32 m0, s0
	ds_read_b128 v[152:155], v252 offset:16384
	ds_read_b128 v[156:159], v252 offset:17408
	ds_read_b128 v[160:163], v252 offset:18432
	ds_read_b128 v[164:167], v252 offset:19456
	ds_read_b128 v[172:175], v252 offset:20480
	ds_read_b128 v[184:187], v252 offset:21504
	ds_read_b128 v[188:191], v252 offset:22528
	ds_read_b128 v[192:195], v252 offset:23552
	global_load_lds_dwordx4 v2, s[12:13]
	s_add_i32 m0, s0, 0x2000
	s_add_u32 s0, s12, 0x168000
	s_addc_u32 s1, s13, 0
	s_add_i32 s15, s16, s51
	global_load_lds_dwordx4 v214, s[12:13]
	s_mov_b32 m0, s15
	s_nop 0
	global_load_lds_dwordx4 v2, s[0:1]
	s_add_i32 m0, s15, 0x2000
	s_nop 0
	global_load_lds_dwordx4 v214, s[0:1]
	s_mov_b32 m0, s52
	s_nop 0
	global_load_lds_dwordx4 v210, s[22:23]
	s_mov_b32 m0, s53
	s_nop 0
	global_load_lds_dwordx4 v212, s[22:23]
	s_waitcnt vmcnt(8)
	s_waitcnt lgkmcnt(0)
	s_barrier
	s_waitcnt lgkmcnt(0)
	v_mfma_f32_16x16x32_bf16 v[80:83], v[56:59], v[152:155], v[80:83]
	v_mfma_f32_16x16x32_bf16 v[80:83], v[60:63], v[156:159], v[80:83]
	v_mfma_f32_16x16x32_bf16 v[76:79], v[72:75], v[156:159], v[76:79]
	v_mfma_f32_16x16x32_bf16 v[76:79], v[68:71], v[152:155], v[76:79]
	v_mfma_f32_16x16x32_bf16 v[44:47], v[68:71], v[160:163], v[44:47]
	v_mfma_f32_16x16x32_bf16 v[44:47], v[72:75], v[164:167], v[44:47]
	v_mfma_f32_16x16x32_bf16 v[48:51], v[60:63], v[164:167], v[48:51]
	v_mfma_f32_16x16x32_bf16 v[48:51], v[56:59], v[160:163], v[48:51]
	v_mfma_f32_16x16x32_bf16 v[32:35], v[56:59], v[172:175], v[32:35]
	v_mfma_f32_16x16x32_bf16 v[32:35], v[60:63], v[184:187], v[32:35]
	v_mfma_f32_16x16x32_bf16 v[28:31], v[72:75], v[184:187], v[28:31]
	v_mfma_f32_16x16x32_bf16 v[28:31], v[68:71], v[172:175], v[28:31]
	v_mfma_f32_16x16x32_bf16 v[12:15], v[68:71], v[188:191], v[12:15]
	v_mfma_f32_16x16x32_bf16 v[12:15], v[72:75], v[192:195], v[12:15]
	v_mfma_f32_16x16x32_bf16 v[16:19], v[60:63], v[192:195], v[16:19]
	v_mfma_f32_16x16x32_bf16 v[16:19], v[56:59], v[188:191], v[16:19]
	v_mfma_f32_16x16x32_bf16 v[52:55], v[116:119], v[152:155], v[52:55]
	v_mfma_f32_16x16x32_bf16 v[40:43], v[92:95], v[160:163], v[40:43]
	v_mfma_f32_16x16x32_bf16 v[36:39], v[116:119], v[160:163], v[36:39]
	v_mfma_f32_16x16x32_bf16 v[24:27], v[92:95], v[172:175], v[24:27]
	v_mfma_f32_16x16x32_bf16 v[20:23], v[116:119], v[172:175], v[20:23]
	v_mfma_f32_16x16x32_bf16 v[8:11], v[92:95], v[188:191], v[8:11]
	v_mfma_f32_16x16x32_bf16 v[4:7], v[116:119], v[188:191], v[4:7]
	v_mfma_f32_16x16x32_bf16 v[56:59], v[92:95], v[152:155], v[64:67]
	v_mfma_f32_16x16x32_bf16 v[52:55], v[128:131], v[156:159], v[52:55]
	v_mfma_f32_16x16x32_bf16 v[40:43], v[104:107], v[164:167], v[40:43]
	v_mfma_f32_16x16x32_bf16 v[36:39], v[128:131], v[164:167], v[36:39]
	v_mfma_f32_16x16x32_bf16 v[24:27], v[104:107], v[184:187], v[24:27]
	v_mfma_f32_16x16x32_bf16 v[20:23], v[128:131], v[184:187], v[20:23]
	v_mfma_f32_16x16x32_bf16 v[8:11], v[104:107], v[192:195], v[8:11]
	v_mfma_f32_16x16x32_bf16 v[4:7], v[128:131], v[192:195], v[4:7]
	v_mfma_f32_16x16x32_bf16 v[56:59], v[104:107], v[156:159], v[56:59]
	s_barrier
; #define PG8_STAGE(bufoff, gbase, voff) do { _Pragma("unroll") for (int _i = 0; _i < 2; ++_i) \
;         __builtin_amdgcn_global_load_lds((const unsigned*)((const char*)(gbase) + (voff)[_i]), (PG8_LAS unsigned*)(lds + (bufoff) + ldsw + _i * 8192), 16, 0, 0); } while (0)
; #define PG8_LDA(dst, b, h) do { _Pragma("unroll") for (int m = 0; m < 4; ++m) _Pragma("unroll") for (int k = 0; k < 2; ++k) dst[m][k] = *(const PG8_LAS bf16x8*)(lds + PG8_SA(b, h) + aoff + m * 2048 + k * 1024); } while (0)
; #define PG8_LDB(dst, b, h) do { _Pragma("unroll") for (int n = 0; n < 2; ++n) _Pragma("unroll") for (int k = 0; k < 2; ++k) dst[n][k] = *(const PG8_LAS bf16x8*)(lds + PG8_SB(b, h) + boff + n * 2048 + k * 1024); } while (0)
; #define PG8_MMA(ai, bj, At, Bt) do { __builtin_amdgcn_s_setprio(1); _Pragma("unroll") for (int m = 0; m < 4; ++m) _Pragma("unroll") for (int n = 0; n < 2; ++n) _Pragma("unroll") for (int k = 0; k < 2; ++k) \
;         acc[ai][bj][m][n] = __builtin_amdgcn_mfma_f32_16x16x32_bf16(Bt[n][k], At[m][k], acc[ai][bj][m][n], 0, 0, 0); __builtin_amdgcn_s_setprio(0); } while (0)
; #define PG8_WAIT_V(n) asm volatile("s_waitcnt vmcnt(" #n ")" ::: "memory")
; #define PG8_WAIT_L(n) asm volatile("s_waitcnt lgkmcnt(" #n ")" ::: "memory")
; #define PG8_BAR __builtin_amdgcn_s_barrier()
; #define PG8_SCHED __builtin_amdgcn_sched_barrier(0)
; template <class Epi, class Sched, bool ALIGN_EPI = true>
; __device__ __forceinline__ void gemm_phase(PG8_LAS unsigned char* lds, const Gemm g, const Sched& S, const Epi& E, const int tid) {
;     ...
;             PG8_LDB(B0, 1, 0); PG8_LDB(B1, 1, 1); PG8_SCHED; PG8_LDA(At, 1, 0); PG8_STAGE(PG8_SA(0, 1), a2 + hstepA, voffA);
;             PG8_WAIT_V(8); PG8_WAIT_L(0); PG8_BAR; PG8_MMA(0, 0, At, B0); PG8_MMA(0, 1, At, B1); PG8_BAR; PG8_SCHED;
;             PG8_LDA(At, 1, 1); PG8_STAGE(PG8_SB(1, 0), b3, voffB); PG8_STAGE(PG8_SB(1, 1), b3 + hstepB, voffB); PG8_STAGE(PG8_SA(1, 0), a3, voffA);
;             PG8_WAIT_V(8); PG8_WAIT_L(0); PG8_BAR; PG8_MMA(1, 0, At, B0); PG8_MMA(1, 1, At, B1); PG8_BAR; PG8_SCHED;
;         }
;         if constexpr (ALIGN_EPI) { if (wr == 0) PG8_BAR; }
;         E(acc, cur, wr, wc, fr, fq); S.done(cur);
;         if (!has_next) break;
	s_add_i32 s15, 0, 0x18000
	s_add_i32 s16, 0, 0x1c000
	v_add_u32_e32 v72, s15, v251
	v_add_u32_e32 v128, s16, v251
	ds_read_b128 v[60:63], v72
	ds_read_b128 v[64:67], v72 offset:1024
	ds_read_b128 v[68:71], v72 offset:2048
	ds_read_b128 v[72:75], v72 offset:3072
	ds_read_b128 v[92:95], v128
	ds_read_b128 v[104:107], v128 offset:1024
	ds_read_b128 v[116:119], v128 offset:2048
	ds_read_b128 v[128:131], v128 offset:3072
	s_add_u32 s0, s22, 0x168000
	s_addc_u32 s1, s23, 0
	s_mov_b32 m0, s54
	ds_read_b128 v[152:155], v252 offset:32768
	ds_read_b128 v[156:159], v252 offset:33792
	ds_read_b128 v[160:163], v252 offset:34816
	ds_read_b128 v[172:175], v252 offset:35840
	ds_read_b128 v[184:187], v252 offset:36864
	ds_read_b128 v[188:191], v252 offset:37888
	ds_read_b128 v[192:195], v252 offset:38912
	ds_read_b128 v[196:199], v252 offset:39936
	global_load_lds_dwordx4 v210, s[0:1]
	s_mov_b32 m0, s55
	s_nop 0
	global_load_lds_dwordx4 v212, s[0:1]
	s_waitcnt vmcnt(8)
	s_waitcnt lgkmcnt(0)
	s_barrier
	s_waitcnt lgkmcnt(0)
	v_mfma_f32_16x16x32_bf16 v[164:167], v[60:63], v[152:155], v[180:183]
	v_mfma_f32_16x16x32_bf16 v[180:183], v[64:67], v[156:159], v[164:167]
	v_mfma_f32_16x16x32_bf16 v[164:167], v[68:71], v[152:155], v[176:179]
	v_mfma_f32_16x16x32_bf16 v[148:151], v[60:63], v[160:163], v[148:151]
	v_mfma_f32_16x16x32_bf16 v[144:147], v[68:71], v[160:163], v[144:147]
	v_mfma_f32_16x16x32_bf16 v[124:127], v[60:63], v[184:187], v[124:127]
	v_mfma_f32_16x16x32_bf16 v[120:123], v[68:71], v[184:187], v[120:123]
	v_mfma_f32_16x16x32_bf16 v[100:103], v[60:63], v[192:195], v[100:103]
	v_mfma_f32_16x16x32_bf16 v[96:99], v[68:71], v[192:195], v[96:99]
	v_mfma_f32_16x16x32_bf16 v[176:179], v[72:75], v[156:159], v[164:167]
	v_mfma_f32_16x16x32_bf16 v[148:151], v[64:67], v[172:175], v[148:151]
	v_mfma_f32_16x16x32_bf16 v[144:147], v[72:75], v[172:175], v[144:147]
	v_mfma_f32_16x16x32_bf16 v[124:127], v[64:67], v[188:191], v[124:127]
	v_mfma_f32_16x16x32_bf16 v[120:123], v[72:75], v[188:191], v[120:123]
	v_mfma_f32_16x16x32_bf16 v[100:103], v[64:67], v[196:199], v[100:103]
	v_mfma_f32_16x16x32_bf16 v[96:99], v[72:75], v[196:199], v[96:99]
	v_mfma_f32_16x16x32_bf16 v[164:167], v[92:95], v[152:155], v[168:171]
	v_mfma_f32_16x16x32_bf16 v[140:143], v[116:119], v[152:155], v[140:143]
	v_mfma_f32_16x16x32_bf16 v[136:139], v[92:95], v[160:163], v[136:139]
	v_mfma_f32_16x16x32_bf16 v[132:135], v[116:119], v[160:163], v[132:135]
	v_mfma_f32_16x16x32_bf16 v[112:115], v[92:95], v[184:187], v[112:115]
	v_mfma_f32_16x16x32_bf16 v[108:111], v[116:119], v[184:187], v[108:111]
	v_mfma_f32_16x16x32_bf16 v[88:91], v[92:95], v[192:195], v[88:91]
	v_mfma_f32_16x16x32_bf16 v[84:87], v[116:119], v[192:195], v[84:87]
	v_mfma_f32_16x16x32_bf16 v[168:171], v[104:107], v[156:159], v[164:167]
	v_mfma_f32_16x16x32_bf16 v[164:167], v[128:131], v[156:159], v[140:143]
	v_mfma_f32_16x16x32_bf16 v[136:139], v[104:107], v[172:175], v[136:139]
	v_mfma_f32_16x16x32_bf16 v[132:135], v[128:131], v[172:175], v[132:135]
	v_mfma_f32_16x16x32_bf16 v[112:115], v[104:107], v[188:191], v[112:115]
	v_mfma_f32_16x16x32_bf16 v[108:111], v[128:131], v[188:191], v[108:111]
	v_mfma_f32_16x16x32_bf16 v[88:91], v[104:107], v[196:199], v[88:91]
	v_mfma_f32_16x16x32_bf16 v[84:87], v[128:131], v[196:199], v[84:87]
	s_barrier
	s_add_i32 s0, s15, s51
	s_mov_b32 m0, s0
	ds_read_b128 v[140:143], v252 offset:49152
	ds_read_b128 v[152:155], v252 offset:50176
	ds_read_b128 v[156:159], v252 offset:51200
	ds_read_b128 v[160:163], v252 offset:52224
	ds_read_b128 v[172:175], v252 offset:53248
	ds_read_b128 v[184:187], v252 offset:54272
	ds_read_b128 v[188:191], v252 offset:55296
	ds_read_b128 v[192:195], v252 offset:56320
	s_add_u32 s98, s12, 0x80
	s_addc_u32 s99, s13, 0
	global_load_lds_dwordx4 v2, s[98:99]
	s_add_i32 m0, s0, 0x2000
	s_add_u32 s0, s12, 0x168080
	s_addc_u32 s1, s13, 0
	s_add_i32 s12, s16, s51
	global_load_lds_dwordx4 v214, s[98:99]
	s_mov_b32 m0, s12
	s_nop 0
	global_load_lds_dwordx4 v2, s[0:1]
	s_add_i32 m0, s12, 0x2000
	s_nop 0
	global_load_lds_dwordx4 v214, s[0:1]
	s_mov_b32 m0, s58
	s_nop 0
	s_add_u32 s98, s22, 0x80
	s_addc_u32 s99, s23, 0
	global_load_lds_dwordx4 v210, s[98:99]
	s_mov_b32 m0, s59
	s_nop 0
	global_load_lds_dwordx4 v212, s[98:99]
	s_waitcnt vmcnt(8)
	s_waitcnt lgkmcnt(0)
	s_barrier
	s_waitcnt lgkmcnt(0)
	v_mfma_f32_16x16x32_bf16 v[80:83], v[60:63], v[140:143], v[80:83]
	v_mfma_f32_16x16x32_bf16 v[80:83], v[64:67], v[152:155], v[80:83]
	v_mfma_f32_16x16x32_bf16 v[76:79], v[72:75], v[152:155], v[76:79]
	v_mfma_f32_16x16x32_bf16 v[76:79], v[68:71], v[140:143], v[76:79]
	v_mfma_f32_16x16x32_bf16 v[44:47], v[68:71], v[156:159], v[44:47]
	v_mfma_f32_16x16x32_bf16 v[44:47], v[72:75], v[160:163], v[44:47]
	v_mfma_f32_16x16x32_bf16 v[48:51], v[64:67], v[160:163], v[48:51]
	v_mfma_f32_16x16x32_bf16 v[48:51], v[60:63], v[156:159], v[48:51]
	v_mfma_f32_16x16x32_bf16 v[32:35], v[60:63], v[172:175], v[32:35]
	v_mfma_f32_16x16x32_bf16 v[32:35], v[64:67], v[184:187], v[32:35]
	v_mfma_f32_16x16x32_bf16 v[28:31], v[72:75], v[184:187], v[28:31]
	v_mfma_f32_16x16x32_bf16 v[28:31], v[68:71], v[172:175], v[28:31]
	v_mfma_f32_16x16x32_bf16 v[12:15], v[68:71], v[188:191], v[12:15]
	v_mfma_f32_16x16x32_bf16 v[12:15], v[72:75], v[192:195], v[12:15]
	v_mfma_f32_16x16x32_bf16 v[16:19], v[64:67], v[192:195], v[16:19]
	v_mfma_f32_16x16x32_bf16 v[16:19], v[60:63], v[188:191], v[16:19]
	v_mfma_f32_16x16x32_bf16 v[56:59], v[92:95], v[140:143], v[56:59]
	v_mfma_f32_16x16x32_bf16 v[52:55], v[116:119], v[140:143], v[52:55]
	v_mfma_f32_16x16x32_bf16 v[40:43], v[92:95], v[156:159], v[40:43]
	v_mfma_f32_16x16x32_bf16 v[36:39], v[116:119], v[156:159], v[36:39]
	v_mfma_f32_16x16x32_bf16 v[24:27], v[92:95], v[172:175], v[24:27]
	v_mfma_f32_16x16x32_bf16 v[20:23], v[116:119], v[172:175], v[20:23]
	v_mfma_f32_16x16x32_bf16 v[8:11], v[92:95], v[188:191], v[8:11]
	v_mfma_f32_16x16x32_bf16 v[4:7], v[116:119], v[188:191], v[4:7]
	v_mfma_f32_16x16x32_bf16 v[64:67], v[104:107], v[152:155], v[56:59]
	v_mfma_f32_16x16x32_bf16 v[52:55], v[128:131], v[152:155], v[52:55]
	v_mfma_f32_16x16x32_bf16 v[40:43], v[104:107], v[160:163], v[40:43]
	v_mfma_f32_16x16x32_bf16 v[36:39], v[128:131], v[160:163], v[36:39]
	v_mfma_f32_16x16x32_bf16 v[24:27], v[104:107], v[184:187], v[24:27]
	v_mfma_f32_16x16x32_bf16 v[20:23], v[128:131], v[184:187], v[20:23]
	v_mfma_f32_16x16x32_bf16 v[8:11], v[104:107], v[192:195], v[8:11]
	v_mfma_f32_16x16x32_bf16 v[4:7], v[128:131], v[192:195], v[4:7]
	s_barrier
	s_add_u32 s68, s68, 0x100
	s_addc_u32 s69, s69, 0
	s_cmp_ge_i32 s70, s67
	s_mov_b64 s[0:1], s[10:11]
	s_mov_b32 s12, s70
	s_cbranch_scc0 .LBB0_1414
	s_nop 0
	s_nop 0
	s_nop 0
	s_nop 0
	s_nop 0
	s_nop 0
	s_nop 0
	s_nop 0
	s_nop 0
	s_nop 0
	s_nop 0
	s_nop 0
	s_and_b64 vcc, exec, s[42:43]
	s_cbranch_vccz .LBB0_1417
	s_barrier
